# plus: attention unit order groups the 4 query heads of a kv head per 4 waves; first K-loop trip peeled with SrcC=0 (no accumulator clears)
# speedup vs baseline: 1.0344x; 1.0071x over previous
.LBB0_122:
	v_mov_b64_e32 v[0:1], 0x180
	s_ashr_i32 s15, s14, 31
	v_cmp_lt_i64_e32 vcc, s[16:17], v[0:1]
	s_lshl_b64 s[16:17], s[14:15], 19
	s_add_u32 s16, s30, s16
	s_addc_u32 s17, s31, s17
	s_and_b64 s[18:19], vcc, exec
	s_cselect_b32 s7, s17, s21
	s_cselect_b32 s9, s16, s20
	s_ashr_i32 s13, s12, 31
	s_lshl_b64 s[18:19], s[12:13], 19
	s_add_u32 s18, s34, s18
	s_addc_u32 s19, s35, s19
	s_and_b64 s[22:23], vcc, exec
	s_cselect_b32 s13, s19, s3
	s_cselect_b32 s15, s18, s2
	s_add_u32 s20, s20, 0x40080
	s_addc_u32 s21, s21, 0
	s_add_u32 s50, s2, 0x100
	s_addc_u32 s51, s3, 0
	s_mov_b32 s52, -2
	s_add_u32 s2, s20, 0xfffc0080
	s_addc_u32 s3, s21, -1
	s_add_i32 s53, 0, 0x10000
	v_add_u32_e32 v36, s53, v164
	ds_read_b128 v[24:27], v36
	ds_read_b128 v[28:31], v36 offset:1024
	ds_read_b128 v[32:35], v36 offset:2048
	ds_read_b128 v[36:39], v36 offset:3072
	s_cmp_eq_u32 s52, 12
	s_cselect_b32 s23, s7, s3
	s_cselect_b32 s22, s9, s2
	s_cselect_b32 s3, s13, s51
	s_cselect_b32 s2, s15, s50
	v_lshl_add_u64 v[166:167], s[20:21], 0, v[150:151]
	s_add_i32 m0, s37, 0xc000
	ds_read_b128 v[154:157], v165
	ds_read_b128 v[158:161], v165 offset:1024
	ds_read_b128 v[180:183], v165 offset:2048
	ds_read_b128 v[184:187], v165 offset:3072
	ds_read_b128 v[188:191], v165 offset:4096
	ds_read_b128 v[192:195], v165 offset:5120
	ds_read_b128 v[196:199], v165 offset:6144
	ds_read_b128 v[200:203], v165 offset:7168
	global_load_lds_dwordx4 v[166:167], off
	v_lshl_add_u64 v[166:167], s[20:21], 0, v[152:153]
	s_add_i32 m0, s37, 0xe000
	s_nop 0
	global_load_lds_dwordx4 v[166:167], off
	s_waitcnt lgkmcnt(8)
	s_barrier
	s_waitcnt lgkmcnt(0)
	s_setprio 1
	s_waitcnt lgkmcnt(0)
	v_mfma_f32_16x16x32_bf16 v[140:143], v[24:27], v[154:157], 0
	v_mfma_f32_16x16x32_bf16 v[136:139], v[32:35], v[154:157], 0
	v_mfma_f32_16x16x32_bf16 v[124:127], v[24:27], v[180:183], 0
	v_mfma_f32_16x16x32_bf16 v[120:123], v[32:35], v[180:183], 0
	v_mfma_f32_16x16x32_bf16 v[108:111], v[24:27], v[188:191], 0
	v_mfma_f32_16x16x32_bf16 v[104:107], v[32:35], v[188:191], 0
	v_mfma_f32_16x16x32_bf16 v[92:95], v[24:27], v[196:199], 0
	v_mfma_f32_16x16x32_bf16 v[88:91], v[32:35], v[196:199], 0
	v_mfma_f32_16x16x32_bf16 v[140:143], v[28:31], v[158:161], v[140:143]
	v_mfma_f32_16x16x32_bf16 v[136:139], v[36:39], v[158:161], v[136:139]
	v_mfma_f32_16x16x32_bf16 v[124:127], v[28:31], v[184:187], v[124:127]
	v_mfma_f32_16x16x32_bf16 v[120:123], v[36:39], v[184:187], v[120:123]
	v_mfma_f32_16x16x32_bf16 v[108:111], v[28:31], v[192:195], v[108:111]
	v_mfma_f32_16x16x32_bf16 v[104:107], v[36:39], v[192:195], v[104:107]
	v_mfma_f32_16x16x32_bf16 v[92:95], v[28:31], v[200:203], v[92:95]
	v_mfma_f32_16x16x32_bf16 v[88:91], v[36:39], v[200:203], v[88:91]
	s_setprio 0
	s_barrier
	s_add_i32 s56, 0, 0x14000
	v_add_u32_e32 v166, s56, v164
	s_add_i32 s53, s53, s36
	ds_read_b128 v[204:207], v166
	ds_read_b128 v[208:211], v166 offset:1024
	ds_read_b128 v[212:215], v166 offset:2048
	ds_read_b128 v[216:219], v166 offset:3072
	v_lshl_add_u64 v[166:167], s[2:3], 0, v[168:169]
	s_mov_b32 m0, s53
	v_lshl_add_u64 v[220:221], s[2:3], 0, v[148:149]
	global_load_lds_dwordx4 v[166:167], off
	s_add_i32 m0, s53, 0x2000
	s_nop 0
	global_load_lds_dwordx4 v[220:221], off
	s_barrier
	s_waitcnt lgkmcnt(0)
	s_setprio 1
	s_waitcnt lgkmcnt(0)
	v_mfma_f32_16x16x32_bf16 v[132:135], v[204:207], v[154:157], 0
	v_mfma_f32_16x16x32_bf16 v[128:131], v[212:215], v[154:157], 0
	v_mfma_f32_16x16x32_bf16 v[116:119], v[204:207], v[180:183], 0
	v_mfma_f32_16x16x32_bf16 v[112:115], v[212:215], v[180:183], 0
	v_mfma_f32_16x16x32_bf16 v[100:103], v[204:207], v[188:191], 0
	v_mfma_f32_16x16x32_bf16 v[96:99], v[212:215], v[188:191], 0
	v_mfma_f32_16x16x32_bf16 v[84:87], v[204:207], v[196:199], 0
	v_mfma_f32_16x16x32_bf16 v[80:83], v[212:215], v[196:199], 0
	v_mfma_f32_16x16x32_bf16 v[132:135], v[208:211], v[158:161], v[132:135]
	v_mfma_f32_16x16x32_bf16 v[128:131], v[216:219], v[158:161], v[128:131]
	v_mfma_f32_16x16x32_bf16 v[116:119], v[208:211], v[184:187], v[116:119]
	v_mfma_f32_16x16x32_bf16 v[112:115], v[216:219], v[184:187], v[112:115]
	v_mfma_f32_16x16x32_bf16 v[100:103], v[208:211], v[192:195], v[100:103]
	v_mfma_f32_16x16x32_bf16 v[96:99], v[216:219], v[192:195], v[96:99]
	v_mfma_f32_16x16x32_bf16 v[84:87], v[208:211], v[200:203], v[84:87]
	v_mfma_f32_16x16x32_bf16 v[80:83], v[216:219], v[200:203], v[80:83]
	s_setprio 0
	s_mov_b32 m0, s37
	v_lshl_add_u64 v[222:223], s[22:23], 0, v[144:145]
	s_barrier
	ds_read_b128 v[154:157], v165 offset:16384
	ds_read_b128 v[158:161], v165 offset:17408
	ds_read_b128 v[180:183], v165 offset:18432
	ds_read_b128 v[184:187], v165 offset:19456
	ds_read_b128 v[188:191], v165 offset:20480
	ds_read_b128 v[192:195], v165 offset:21504
	ds_read_b128 v[196:199], v165 offset:22528
	ds_read_b128 v[200:203], v165 offset:23552
	global_load_lds_dwordx4 v[222:223], off
	v_lshl_add_u64 v[236:237], s[22:23], 0, v[146:147]
	s_mov_b32 m0, s38
	s_nop 0
	global_load_lds_dwordx4 v[236:237], off
	s_barrier
	s_waitcnt lgkmcnt(0)
	s_setprio 1
	s_waitcnt lgkmcnt(0)
	v_mfma_f32_16x16x32_bf16 v[76:79], v[24:27], v[154:157], 0
	v_mfma_f32_16x16x32_bf16 v[72:75], v[32:35], v[154:157], 0
	v_mfma_f32_16x16x32_bf16 v[60:63], v[24:27], v[180:183], 0
	v_mfma_f32_16x16x32_bf16 v[56:59], v[32:35], v[180:183], 0
	v_mfma_f32_16x16x32_bf16 v[44:47], v[24:27], v[188:191], 0
	v_mfma_f32_16x16x32_bf16 v[40:43], v[32:35], v[188:191], 0
	v_mfma_f32_16x16x32_bf16 v[12:15], v[24:27], v[196:199], 0
	v_mfma_f32_16x16x32_bf16 v[8:11], v[32:35], v[196:199], 0
	v_mfma_f32_16x16x32_bf16 v[76:79], v[28:31], v[158:161], v[76:79]
	v_mfma_f32_16x16x32_bf16 v[72:75], v[36:39], v[158:161], v[72:75]
	v_mfma_f32_16x16x32_bf16 v[60:63], v[28:31], v[184:187], v[60:63]
	v_mfma_f32_16x16x32_bf16 v[56:59], v[36:39], v[184:187], v[56:59]
	v_mfma_f32_16x16x32_bf16 v[44:47], v[28:31], v[192:195], v[44:47]
	v_mfma_f32_16x16x32_bf16 v[40:43], v[36:39], v[192:195], v[40:43]
	v_mfma_f32_16x16x32_bf16 v[12:15], v[28:31], v[200:203], v[12:15]
	v_mfma_f32_16x16x32_bf16 v[8:11], v[36:39], v[200:203], v[8:11]
	s_setprio 0
	s_barrier
	s_add_u32 s54, s2, 0x40000
	s_addc_u32 s55, s3, 0
	s_add_i32 s53, s56, s36
	v_lshl_add_u64 v[24:25], s[54:55], 0, v[168:169]
	s_mov_b32 m0, s53
	s_nop 0
	global_load_lds_dwordx4 v[24:25], off
	v_lshl_add_u64 v[24:25], s[54:55], 0, v[148:149]
	s_add_i32 m0, s53, 0x2000
	s_nop 0
	global_load_lds_dwordx4 v[24:25], off
	s_waitcnt vmcnt(6)
	s_barrier
	s_setprio 1
	v_mfma_f32_16x16x32_bf16 v[20:23], v[204:207], v[188:191], 0
	v_mfma_f32_16x16x32_bf16 v[16:19], v[212:215], v[188:191], 0
	v_mfma_f32_16x16x32_bf16 v[4:7], v[204:207], v[196:199], 0
	v_mfma_f32_16x16x32_bf16 v[0:3], v[212:215], v[196:199], 0
	v_mfma_f32_16x16x32_bf16 v[24:27], v[204:207], v[154:157], 0
	v_mfma_f32_16x16x32_bf16 v[28:31], v[212:215], v[154:157], 0
	v_mfma_f32_16x16x32_bf16 v[32:35], v[204:207], v[180:183], 0
	v_mfma_f32_16x16x32_bf16 v[36:39], v[212:215], v[180:183], 0
	v_mfma_f32_16x16x32_bf16 v[20:23], v[208:211], v[192:195], v[20:23]
	v_mfma_f32_16x16x32_bf16 v[16:19], v[216:219], v[192:195], v[16:19]
	v_mfma_f32_16x16x32_bf16 v[4:7], v[208:211], v[200:203], v[4:7]
	v_mfma_f32_16x16x32_bf16 v[0:3], v[216:219], v[200:203], v[0:3]
	v_mfma_f32_16x16x32_bf16 v[24:27], v[208:211], v[158:161], v[24:27]
	v_mfma_f32_16x16x32_bf16 v[28:31], v[216:219], v[158:161], v[28:31]
	v_mfma_f32_16x16x32_bf16 v[32:35], v[208:211], v[184:187], v[32:35]
	v_mfma_f32_16x16x32_bf16 v[36:39], v[216:219], v[184:187], v[36:39]
	s_setprio 0
	s_add_i32 s53, 0, 0x18000
	v_add_u32_e32 v68, s53, v164
	s_barrier
	ds_read_b128 v[48:51], v68
	ds_read_b128 v[52:55], v68 offset:1024
	ds_read_b128 v[64:67], v68 offset:2048
	ds_read_b128 v[68:71], v68 offset:3072
	s_add_u32 s22, s22, 0x40000
	s_addc_u32 s23, s23, 0
	s_mov_b32 m0, s39
	v_lshl_add_u64 v[204:205], s[22:23], 0, v[144:145]
	ds_read_b128 v[154:157], v165 offset:32768
	ds_read_b128 v[158:161], v165 offset:33792
	ds_read_b128 v[180:183], v165 offset:34816
	ds_read_b128 v[184:187], v165 offset:35840
	ds_read_b128 v[188:191], v165 offset:36864
	ds_read_b128 v[192:195], v165 offset:37888
	ds_read_b128 v[196:199], v165 offset:38912
	ds_read_b128 v[200:203], v165 offset:39936
	global_load_lds_dwordx4 v[204:205], off
	v_lshl_add_u64 v[204:205], s[22:23], 0, v[146:147]
	s_mov_b32 m0, s40
	s_nop 0
	global_load_lds_dwordx4 v[204:205], off
	s_waitcnt lgkmcnt(8)
	s_barrier
	s_waitcnt lgkmcnt(0)
	s_setprio 1
	s_waitcnt lgkmcnt(0)
	v_mfma_f32_16x16x32_bf16 v[140:143], v[48:51], v[154:157], v[140:143]
	v_mfma_f32_16x16x32_bf16 v[136:139], v[64:67], v[154:157], v[136:139]
	v_mfma_f32_16x16x32_bf16 v[124:127], v[48:51], v[180:183], v[124:127]
	v_mfma_f32_16x16x32_bf16 v[120:123], v[64:67], v[180:183], v[120:123]
	v_mfma_f32_16x16x32_bf16 v[108:111], v[48:51], v[188:191], v[108:111]
	v_mfma_f32_16x16x32_bf16 v[104:107], v[64:67], v[188:191], v[104:107]
	v_mfma_f32_16x16x32_bf16 v[92:95], v[48:51], v[196:199], v[92:95]
	v_mfma_f32_16x16x32_bf16 v[88:91], v[64:67], v[196:199], v[88:91]
	v_mfma_f32_16x16x32_bf16 v[140:143], v[52:55], v[158:161], v[140:143]
	v_mfma_f32_16x16x32_bf16 v[136:139], v[68:71], v[158:161], v[136:139]
	v_mfma_f32_16x16x32_bf16 v[124:127], v[52:55], v[184:187], v[124:127]
	v_mfma_f32_16x16x32_bf16 v[120:123], v[68:71], v[184:187], v[120:123]
	v_mfma_f32_16x16x32_bf16 v[108:111], v[52:55], v[192:195], v[108:111]
	v_mfma_f32_16x16x32_bf16 v[104:107], v[68:71], v[192:195], v[104:107]
	v_mfma_f32_16x16x32_bf16 v[92:95], v[52:55], v[200:203], v[92:95]
	v_mfma_f32_16x16x32_bf16 v[88:91], v[68:71], v[200:203], v[88:91]
	s_setprio 0
	s_barrier
	s_add_i32 s22, 0, 0x1c000
	s_add_i32 s23, s53, s36
	v_add_u32_e32 v216, s22, v164
	v_lshl_add_u64 v[166:167], v[166:167], 0, s[78:79]
	s_mov_b32 m0, s23
	ds_read_b128 v[204:207], v216
	ds_read_b128 v[208:211], v216 offset:1024
	ds_read_b128 v[212:215], v216 offset:2048
	ds_read_b128 v[216:219], v216 offset:3072
	global_load_lds_dwordx4 v[166:167], off
	v_lshl_add_u64 v[166:167], v[220:221], 0, s[78:79]
	s_add_i32 m0, s23, 0x2000
	s_nop 0
	global_load_lds_dwordx4 v[166:167], off
	s_barrier
	s_waitcnt lgkmcnt(0)
	s_setprio 1
	s_waitcnt lgkmcnt(0)
	v_mfma_f32_16x16x32_bf16 v[132:135], v[204:207], v[154:157], v[132:135]
	v_mfma_f32_16x16x32_bf16 v[128:131], v[212:215], v[154:157], v[128:131]
	v_mfma_f32_16x16x32_bf16 v[116:119], v[204:207], v[180:183], v[116:119]
	v_mfma_f32_16x16x32_bf16 v[112:115], v[212:215], v[180:183], v[112:115]
	v_mfma_f32_16x16x32_bf16 v[100:103], v[204:207], v[188:191], v[100:103]
	v_mfma_f32_16x16x32_bf16 v[96:99], v[212:215], v[188:191], v[96:99]
	v_mfma_f32_16x16x32_bf16 v[84:87], v[204:207], v[196:199], v[84:87]
	v_mfma_f32_16x16x32_bf16 v[80:83], v[212:215], v[196:199], v[80:83]
	v_mfma_f32_16x16x32_bf16 v[132:135], v[208:211], v[158:161], v[132:135]
	v_mfma_f32_16x16x32_bf16 v[128:131], v[216:219], v[158:161], v[128:131]
	v_mfma_f32_16x16x32_bf16 v[116:119], v[208:211], v[184:187], v[116:119]
	v_mfma_f32_16x16x32_bf16 v[112:115], v[216:219], v[184:187], v[112:115]
	v_mfma_f32_16x16x32_bf16 v[100:103], v[208:211], v[192:195], v[100:103]
	v_mfma_f32_16x16x32_bf16 v[96:99], v[216:219], v[192:195], v[96:99]
	v_mfma_f32_16x16x32_bf16 v[84:87], v[208:211], v[200:203], v[84:87]
	v_mfma_f32_16x16x32_bf16 v[80:83], v[216:219], v[200:203], v[80:83]
	s_setprio 0
	s_mov_b32 m0, s45
	v_lshl_add_u64 v[166:167], v[222:223], 0, s[78:79]
	s_barrier
	ds_read_b128 v[154:157], v165 offset:49152
	ds_read_b128 v[158:161], v165 offset:50176
	ds_read_b128 v[180:183], v165 offset:51200
	ds_read_b128 v[184:187], v165 offset:52224
	ds_read_b128 v[188:191], v165 offset:53248
	ds_read_b128 v[192:195], v165 offset:54272
	ds_read_b128 v[196:199], v165 offset:55296
	ds_read_b128 v[200:203], v165 offset:56320
	global_load_lds_dwordx4 v[166:167], off
	v_lshl_add_u64 v[166:167], v[236:237], 0, s[78:79]
	s_mov_b32 m0, s46
	s_nop 0
	global_load_lds_dwordx4 v[166:167], off
	s_barrier
	s_waitcnt lgkmcnt(0)
	s_setprio 1
	s_waitcnt lgkmcnt(0)
	v_mfma_f32_16x16x32_bf16 v[76:79], v[48:51], v[154:157], v[76:79]
	v_mfma_f32_16x16x32_bf16 v[72:75], v[64:67], v[154:157], v[72:75]
	v_mfma_f32_16x16x32_bf16 v[60:63], v[48:51], v[180:183], v[60:63]
	v_mfma_f32_16x16x32_bf16 v[56:59], v[64:67], v[180:183], v[56:59]
	v_mfma_f32_16x16x32_bf16 v[44:47], v[48:51], v[188:191], v[44:47]
	v_mfma_f32_16x16x32_bf16 v[40:43], v[64:67], v[188:191], v[40:43]
	v_mfma_f32_16x16x32_bf16 v[12:15], v[48:51], v[196:199], v[12:15]
	v_mfma_f32_16x16x32_bf16 v[8:11], v[64:67], v[196:199], v[8:11]
	v_mfma_f32_16x16x32_bf16 v[76:79], v[52:55], v[158:161], v[76:79]
	v_mfma_f32_16x16x32_bf16 v[72:75], v[68:71], v[158:161], v[72:75]
	v_mfma_f32_16x16x32_bf16 v[60:63], v[52:55], v[184:187], v[60:63]
	v_mfma_f32_16x16x32_bf16 v[56:59], v[68:71], v[184:187], v[56:59]
	v_mfma_f32_16x16x32_bf16 v[44:47], v[52:55], v[192:195], v[44:47]
	v_mfma_f32_16x16x32_bf16 v[40:43], v[68:71], v[192:195], v[40:43]
	v_mfma_f32_16x16x32_bf16 v[12:15], v[52:55], v[200:203], v[12:15]
	v_mfma_f32_16x16x32_bf16 v[8:11], v[68:71], v[200:203], v[8:11]
	s_setprio 0
	s_barrier
	s_add_u32 s2, s2, 0x40080
	s_addc_u32 s3, s3, 0
	s_add_i32 s22, s22, s36
	v_lshl_add_u64 v[48:49], s[2:3], 0, v[168:169]
	s_mov_b32 m0, s22
	s_nop 0
	global_load_lds_dwordx4 v[48:49], off
	v_lshl_add_u64 v[48:49], s[2:3], 0, v[148:149]
	s_add_i32 m0, s22, 0x2000
	s_nop 0
	global_load_lds_dwordx4 v[48:49], off
	s_waitcnt vmcnt(6)
	s_barrier
	s_setprio 1
	v_mfma_f32_16x16x32_bf16 v[24:27], v[204:207], v[154:157], v[24:27]
	v_mfma_f32_16x16x32_bf16 v[68:71], v[208:211], v[158:161], v[24:27]
	v_mfma_f32_16x16x32_bf16 v[24:27], v[212:215], v[154:157], v[28:31]
	v_mfma_f32_16x16x32_bf16 v[64:67], v[216:219], v[158:161], v[24:27]
	v_mfma_f32_16x16x32_bf16 v[24:27], v[204:207], v[180:183], v[32:35]
	v_mfma_f32_16x16x32_bf16 v[52:55], v[208:211], v[184:187], v[24:27]
	v_mfma_f32_16x16x32_bf16 v[24:27], v[212:215], v[180:183], v[36:39]
	v_mfma_f32_16x16x32_bf16 v[20:23], v[204:207], v[188:191], v[20:23]
	v_mfma_f32_16x16x32_bf16 v[16:19], v[212:215], v[188:191], v[16:19]
	v_mfma_f32_16x16x32_bf16 v[4:7], v[204:207], v[196:199], v[4:7]
	v_mfma_f32_16x16x32_bf16 v[0:3], v[212:215], v[196:199], v[0:3]
	v_mfma_f32_16x16x32_bf16 v[48:51], v[216:219], v[184:187], v[24:27]
	v_mfma_f32_16x16x32_bf16 v[20:23], v[208:211], v[192:195], v[20:23]
	v_mfma_f32_16x16x32_bf16 v[16:19], v[216:219], v[192:195], v[16:19]
	v_mfma_f32_16x16x32_bf16 v[4:7], v[208:211], v[200:203], v[4:7]
	v_mfma_f32_16x16x32_bf16 v[0:3], v[216:219], v[200:203], v[0:3]
	s_setprio 0
	s_add_i32 s52, s52, 2
	s_add_u32 s20, s20, 0x100
	s_addc_u32 s21, s21, 0
	s_add_u32 s50, s50, 0x100
	s_addc_u32 s51, s51, 0
	s_cmp_gt_u32 s52, 13
	s_barrier

.LBB0_354:
	s_ashr_i32 s31, s30, 31
	v_cmp_lt_i64_e32 vcc, s[8:9], v[170:171]
	s_lshl_b64 s[8:9], s[30:31], 19
	s_add_u32 s34, s52, s8
	s_addc_u32 s35, s53, s9
	s_and_b64 s[8:9], vcc, exec
	s_cselect_b32 s1, s35, s7
	s_cselect_b32 s31, s34, s6
	s_ashr_i32 s29, s28, 31
	s_lshl_b64 s[8:9], s[28:29], 19
	s_add_u32 s36, s43, s8
	s_addc_u32 s37, s42, s9
	s_and_b64 s[8:9], vcc, exec
	s_cselect_b32 s29, s37, s3
	s_cselect_b32 s38, s36, s2
	s_add_u32 s6, s6, 0x40080
	s_addc_u32 s7, s7, 0
	s_add_u32 s39, s2, 0x100
	s_addc_u32 s40, s3, 0
	s_mov_b32 s41, -2
	s_add_u32 s2, s6, 0xfffc0080
	s_addc_u32 s3, s7, -1
	s_add_i32 s64, 0, 0x10000
	v_add_u32_e32 v140, s64, v208
	ds_read_b128 v[128:131], v140
	ds_read_b128 v[132:135], v140 offset:1024
	ds_read_b128 v[136:139], v140 offset:2048
	ds_read_b128 v[140:143], v140 offset:3072
	s_cmp_eq_u32 s41, 12
	s_cselect_b32 s9, s1, s3
	s_cselect_b32 s8, s31, s2
	s_cselect_b32 s3, s29, s40
	s_cselect_b32 s2, s38, s39
	v_lshl_add_u64 v[196:197], s[6:7], 0, v[164:165]
	s_add_i32 m0, s21, 0xc000
	ds_read_b128 v[144:147], v209
	ds_read_b128 v[148:151], v209 offset:1024
	ds_read_b128 v[152:155], v209 offset:2048
	ds_read_b128 v[156:159], v209 offset:3072
	ds_read_b128 v[180:183], v209 offset:4096
	ds_read_b128 v[184:187], v209 offset:5120
	ds_read_b128 v[188:191], v209 offset:6144
	ds_read_b128 v[192:195], v209 offset:7168
	global_load_lds_dwordx4 v[196:197], off
	v_lshl_add_u64 v[196:197], s[6:7], 0, v[166:167]
	s_add_i32 m0, s21, 0xe000
	s_nop 0
	global_load_lds_dwordx4 v[196:197], off
	s_waitcnt lgkmcnt(8)
	s_barrier
	s_waitcnt lgkmcnt(0)
	s_setprio 1
	s_waitcnt lgkmcnt(0)
	v_mfma_f32_16x16x32_bf16 v[124:127], v[128:131], v[144:147], 0
	v_mfma_f32_16x16x32_bf16 v[120:123], v[136:139], v[144:147], 0
	v_mfma_f32_16x16x32_bf16 v[116:119], v[128:131], v[152:155], 0
	v_mfma_f32_16x16x32_bf16 v[112:115], v[136:139], v[152:155], 0
	v_mfma_f32_16x16x32_bf16 v[100:103], v[128:131], v[180:183], 0
	v_mfma_f32_16x16x32_bf16 v[96:99], v[136:139], v[180:183], 0
	v_mfma_f32_16x16x32_bf16 v[84:87], v[128:131], v[188:191], 0
	v_mfma_f32_16x16x32_bf16 v[80:83], v[136:139], v[188:191], 0
	v_mfma_f32_16x16x32_bf16 v[124:127], v[132:135], v[148:151], v[124:127]
	v_mfma_f32_16x16x32_bf16 v[120:123], v[140:143], v[148:151], v[120:123]
	v_mfma_f32_16x16x32_bf16 v[116:119], v[132:135], v[156:159], v[116:119]
	v_mfma_f32_16x16x32_bf16 v[112:115], v[140:143], v[156:159], v[112:115]
	v_mfma_f32_16x16x32_bf16 v[100:103], v[132:135], v[184:187], v[100:103]
	v_mfma_f32_16x16x32_bf16 v[96:99], v[140:143], v[184:187], v[96:99]
	v_mfma_f32_16x16x32_bf16 v[84:87], v[132:135], v[192:195], v[84:87]
	v_mfma_f32_16x16x32_bf16 v[80:83], v[140:143], v[192:195], v[80:83]
	s_setprio 0
	s_barrier
	s_add_i32 s66, 0, 0x14000
	s_add_i32 s64, s64, s54
	v_add_u32_e32 v168, s66, v208
	v_lshl_add_u64 v[204:205], s[2:3], 0, v[160:161]
	s_mov_b32 m0, s64
	ds_read_b128 v[196:199], v168
	ds_read_b128 v[200:203], v168 offset:1024
	ds_read_b128 v[210:213], v168 offset:2048
	ds_read_b128 v[214:217], v168 offset:3072
	global_load_lds_dwordx4 v[204:205], off
	v_lshl_add_u64 v[218:219], s[2:3], 0, v[162:163]
	s_add_i32 m0, s64, 0x2000
	s_nop 0
	global_load_lds_dwordx4 v[218:219], off
	s_barrier
	s_waitcnt lgkmcnt(0)
	s_setprio 1
	s_waitcnt lgkmcnt(0)
	v_mfma_f32_16x16x32_bf16 v[108:111], v[196:199], v[144:147], 0
	v_mfma_f32_16x16x32_bf16 v[104:107], v[210:213], v[144:147], 0
	v_mfma_f32_16x16x32_bf16 v[92:95], v[196:199], v[152:155], 0
	v_mfma_f32_16x16x32_bf16 v[88:91], v[210:213], v[152:155], 0
	v_mfma_f32_16x16x32_bf16 v[76:79], v[196:199], v[180:183], 0
	v_mfma_f32_16x16x32_bf16 v[72:75], v[210:213], v[180:183], 0
	v_mfma_f32_16x16x32_bf16 v[68:71], v[196:199], v[188:191], 0
	v_mfma_f32_16x16x32_bf16 v[64:67], v[210:213], v[188:191], 0
	v_mfma_f32_16x16x32_bf16 v[108:111], v[200:203], v[148:151], v[108:111]
	v_mfma_f32_16x16x32_bf16 v[104:107], v[214:217], v[148:151], v[104:107]
	v_mfma_f32_16x16x32_bf16 v[92:95], v[200:203], v[156:159], v[92:95]
	v_mfma_f32_16x16x32_bf16 v[88:91], v[214:217], v[156:159], v[88:91]
	v_mfma_f32_16x16x32_bf16 v[76:79], v[200:203], v[184:187], v[76:79]
	v_mfma_f32_16x16x32_bf16 v[72:75], v[214:217], v[184:187], v[72:75]
	v_mfma_f32_16x16x32_bf16 v[68:71], v[200:203], v[192:195], v[68:71]
	v_mfma_f32_16x16x32_bf16 v[64:67], v[214:217], v[192:195], v[64:67]
	s_setprio 0
	s_mov_b32 m0, s21
	v_lshl_add_u64 v[220:221], s[8:9], 0, v[160:161]
	s_barrier
	ds_read_b128 v[144:147], v209 offset:16384
	ds_read_b128 v[148:151], v209 offset:17408
	ds_read_b128 v[152:155], v209 offset:18432
	ds_read_b128 v[156:159], v209 offset:19456
	ds_read_b128 v[180:183], v209 offset:20480
	ds_read_b128 v[184:187], v209 offset:21504
	ds_read_b128 v[188:191], v209 offset:22528
	ds_read_b128 v[192:195], v209 offset:23552
	global_load_lds_dwordx4 v[220:221], off
	v_lshl_add_u64 v[222:223], s[8:9], 0, v[162:163]
	s_mov_b32 m0, s55
	s_nop 0
	global_load_lds_dwordx4 v[222:223], off
	s_barrier
	s_waitcnt lgkmcnt(0)
	s_setprio 1
	s_waitcnt lgkmcnt(0)
	v_mfma_f32_16x16x32_bf16 v[60:63], v[128:131], v[144:147], 0
	v_mfma_f32_16x16x32_bf16 v[56:59], v[136:139], v[144:147], 0
	v_mfma_f32_16x16x32_bf16 v[52:55], v[128:131], v[152:155], 0
	v_mfma_f32_16x16x32_bf16 v[48:51], v[136:139], v[152:155], 0
	v_mfma_f32_16x16x32_bf16 v[36:39], v[128:131], v[180:183], 0
	v_mfma_f32_16x16x32_bf16 v[32:35], v[136:139], v[180:183], 0
	v_mfma_f32_16x16x32_bf16 v[20:23], v[128:131], v[188:191], 0
	v_mfma_f32_16x16x32_bf16 v[16:19], v[136:139], v[188:191], 0
	v_mfma_f32_16x16x32_bf16 v[60:63], v[132:135], v[148:151], v[60:63]
	v_mfma_f32_16x16x32_bf16 v[56:59], v[140:143], v[148:151], v[56:59]
	v_mfma_f32_16x16x32_bf16 v[52:55], v[132:135], v[156:159], v[52:55]
	v_mfma_f32_16x16x32_bf16 v[48:51], v[140:143], v[156:159], v[48:51]
	v_mfma_f32_16x16x32_bf16 v[36:39], v[132:135], v[184:187], v[36:39]
	v_mfma_f32_16x16x32_bf16 v[32:35], v[140:143], v[184:187], v[32:35]
	v_mfma_f32_16x16x32_bf16 v[20:23], v[132:135], v[192:195], v[20:23]
	v_mfma_f32_16x16x32_bf16 v[16:19], v[140:143], v[192:195], v[16:19]
	s_setprio 0
	s_barrier
	s_add_u32 s64, s2, 0x40000
	s_addc_u32 s65, s3, 0
	s_add_i32 s66, s66, s54
	v_lshl_add_u64 v[128:129], s[64:65], 0, v[160:161]
	s_mov_b32 m0, s66
	s_nop 0
	global_load_lds_dwordx4 v[128:129], off
	v_lshl_add_u64 v[128:129], s[64:65], 0, v[162:163]
	s_add_i32 m0, s66, 0x2000
	s_nop 0
	global_load_lds_dwordx4 v[128:129], off
	s_waitcnt vmcnt(6)
	s_barrier
	s_setprio 1
	v_mfma_f32_16x16x32_bf16 v[44:47], v[196:199], v[144:147], 0
	v_mfma_f32_16x16x32_bf16 v[40:43], v[210:213], v[144:147], 0
	v_mfma_f32_16x16x32_bf16 v[28:31], v[196:199], v[152:155], 0
	v_mfma_f32_16x16x32_bf16 v[24:27], v[210:213], v[152:155], 0
	v_mfma_f32_16x16x32_bf16 v[12:15], v[196:199], v[180:183], 0
	v_mfma_f32_16x16x32_bf16 v[8:11], v[210:213], v[180:183], 0
	v_mfma_f32_16x16x32_bf16 v[4:7], v[196:199], v[188:191], 0
	v_mfma_f32_16x16x32_bf16 v[0:3], v[210:213], v[188:191], 0
	v_mfma_f32_16x16x32_bf16 v[44:47], v[200:203], v[148:151], v[44:47]
	v_mfma_f32_16x16x32_bf16 v[40:43], v[214:217], v[148:151], v[40:43]
	v_mfma_f32_16x16x32_bf16 v[28:31], v[200:203], v[156:159], v[28:31]
	v_mfma_f32_16x16x32_bf16 v[24:27], v[214:217], v[156:159], v[24:27]
	v_mfma_f32_16x16x32_bf16 v[12:15], v[200:203], v[184:187], v[12:15]
	v_mfma_f32_16x16x32_bf16 v[8:11], v[214:217], v[184:187], v[8:11]
	v_mfma_f32_16x16x32_bf16 v[4:7], v[200:203], v[192:195], v[4:7]
	v_mfma_f32_16x16x32_bf16 v[0:3], v[214:217], v[192:195], v[0:3]
	s_setprio 0
	s_add_i32 s64, 0, 0x18000
	v_add_u32_e32 v140, s64, v208
	s_barrier
	ds_read_b128 v[128:131], v140
	ds_read_b128 v[132:135], v140 offset:1024
	ds_read_b128 v[136:139], v140 offset:2048
	ds_read_b128 v[140:143], v140 offset:3072
	s_add_u32 s8, s8, 0x40000
	s_addc_u32 s9, s9, 0
	s_mov_b32 m0, s56
	v_lshl_add_u64 v[196:197], s[8:9], 0, v[160:161]
	ds_read_b128 v[144:147], v209 offset:32768
	ds_read_b128 v[148:151], v209 offset:33792
	ds_read_b128 v[152:155], v209 offset:34816
	ds_read_b128 v[156:159], v209 offset:35840
	ds_read_b128 v[180:183], v209 offset:36864
	ds_read_b128 v[184:187], v209 offset:37888
	ds_read_b128 v[188:191], v209 offset:38912
	ds_read_b128 v[192:195], v209 offset:39936
	global_load_lds_dwordx4 v[196:197], off
	v_lshl_add_u64 v[196:197], s[8:9], 0, v[162:163]
	s_mov_b32 m0, s57
	s_nop 0
	global_load_lds_dwordx4 v[196:197], off
	s_waitcnt lgkmcnt(8)
	s_barrier
	s_waitcnt lgkmcnt(0)
	s_setprio 1
	s_waitcnt lgkmcnt(0)
	v_mfma_f32_16x16x32_bf16 v[124:127], v[128:131], v[144:147], v[124:127]
	v_mfma_f32_16x16x32_bf16 v[120:123], v[136:139], v[144:147], v[120:123]
	v_mfma_f32_16x16x32_bf16 v[116:119], v[128:131], v[152:155], v[116:119]
	v_mfma_f32_16x16x32_bf16 v[112:115], v[136:139], v[152:155], v[112:115]
	v_mfma_f32_16x16x32_bf16 v[100:103], v[128:131], v[180:183], v[100:103]
	v_mfma_f32_16x16x32_bf16 v[96:99], v[136:139], v[180:183], v[96:99]
	v_mfma_f32_16x16x32_bf16 v[84:87], v[128:131], v[188:191], v[84:87]
	v_mfma_f32_16x16x32_bf16 v[80:83], v[136:139], v[188:191], v[80:83]
	v_mfma_f32_16x16x32_bf16 v[124:127], v[132:135], v[148:151], v[124:127]
	v_mfma_f32_16x16x32_bf16 v[120:123], v[140:143], v[148:151], v[120:123]
	v_mfma_f32_16x16x32_bf16 v[116:119], v[132:135], v[156:159], v[116:119]
	v_mfma_f32_16x16x32_bf16 v[112:115], v[140:143], v[156:159], v[112:115]
	v_mfma_f32_16x16x32_bf16 v[100:103], v[132:135], v[184:187], v[100:103]
	v_mfma_f32_16x16x32_bf16 v[96:99], v[140:143], v[184:187], v[96:99]
	v_mfma_f32_16x16x32_bf16 v[84:87], v[132:135], v[192:195], v[84:87]
	v_mfma_f32_16x16x32_bf16 v[80:83], v[140:143], v[192:195], v[80:83]
	s_setprio 0
	s_barrier
	s_add_i32 s8, 0, 0x1c000
	s_add_i32 s9, s64, s54
	v_add_u32_e32 v168, s8, v208
	v_lshl_add_u64 v[204:205], v[204:205], 0, s[78:79]
	s_mov_b32 m0, s9
	ds_read_b128 v[196:199], v168
	ds_read_b128 v[200:203], v168 offset:1024
	ds_read_b128 v[210:213], v168 offset:2048
	ds_read_b128 v[214:217], v168 offset:3072
	global_load_lds_dwordx4 v[204:205], off
	v_lshl_add_u64 v[204:205], v[218:219], 0, s[78:79]
	s_add_i32 m0, s9, 0x2000
	s_nop 0
	global_load_lds_dwordx4 v[204:205], off
	s_barrier
	s_waitcnt lgkmcnt(0)
	s_setprio 1
	s_waitcnt lgkmcnt(0)
	v_mfma_f32_16x16x32_bf16 v[108:111], v[196:199], v[144:147], v[108:111]
	v_mfma_f32_16x16x32_bf16 v[104:107], v[210:213], v[144:147], v[104:107]
	v_mfma_f32_16x16x32_bf16 v[92:95], v[196:199], v[152:155], v[92:95]
	v_mfma_f32_16x16x32_bf16 v[88:91], v[210:213], v[152:155], v[88:91]
	v_mfma_f32_16x16x32_bf16 v[76:79], v[196:199], v[180:183], v[76:79]
	v_mfma_f32_16x16x32_bf16 v[72:75], v[210:213], v[180:183], v[72:75]
	v_mfma_f32_16x16x32_bf16 v[68:71], v[196:199], v[188:191], v[68:71]
	v_mfma_f32_16x16x32_bf16 v[64:67], v[210:213], v[188:191], v[64:67]
	v_mfma_f32_16x16x32_bf16 v[108:111], v[200:203], v[148:151], v[108:111]
	v_mfma_f32_16x16x32_bf16 v[104:107], v[214:217], v[148:151], v[104:107]
	v_mfma_f32_16x16x32_bf16 v[92:95], v[200:203], v[156:159], v[92:95]
	v_mfma_f32_16x16x32_bf16 v[88:91], v[214:217], v[156:159], v[88:91]
	v_mfma_f32_16x16x32_bf16 v[76:79], v[200:203], v[184:187], v[76:79]
	v_mfma_f32_16x16x32_bf16 v[72:75], v[214:217], v[184:187], v[72:75]
	v_mfma_f32_16x16x32_bf16 v[68:71], v[200:203], v[192:195], v[68:71]
	v_mfma_f32_16x16x32_bf16 v[64:67], v[214:217], v[192:195], v[64:67]
	s_setprio 0
	s_mov_b32 m0, s60
	v_lshl_add_u64 v[204:205], v[220:221], 0, s[78:79]
	s_barrier
	ds_read_b128 v[144:147], v209 offset:49152
	ds_read_b128 v[148:151], v209 offset:50176
	ds_read_b128 v[152:155], v209 offset:51200
	ds_read_b128 v[156:159], v209 offset:52224
	ds_read_b128 v[180:183], v209 offset:53248
	ds_read_b128 v[184:187], v209 offset:54272
	ds_read_b128 v[188:191], v209 offset:55296
	ds_read_b128 v[192:195], v209 offset:56320
	global_load_lds_dwordx4 v[204:205], off
	v_lshl_add_u64 v[204:205], v[222:223], 0, s[78:79]
	s_mov_b32 m0, s61
	s_nop 0
	global_load_lds_dwordx4 v[204:205], off
	s_barrier
	s_waitcnt lgkmcnt(0)
	s_setprio 1
	s_waitcnt lgkmcnt(0)
	v_mfma_f32_16x16x32_bf16 v[60:63], v[128:131], v[144:147], v[60:63]
	v_mfma_f32_16x16x32_bf16 v[56:59], v[136:139], v[144:147], v[56:59]
	v_mfma_f32_16x16x32_bf16 v[52:55], v[128:131], v[152:155], v[52:55]
	v_mfma_f32_16x16x32_bf16 v[48:51], v[136:139], v[152:155], v[48:51]
	v_mfma_f32_16x16x32_bf16 v[36:39], v[128:131], v[180:183], v[36:39]
	v_mfma_f32_16x16x32_bf16 v[32:35], v[136:139], v[180:183], v[32:35]
	v_mfma_f32_16x16x32_bf16 v[20:23], v[128:131], v[188:191], v[20:23]
	v_mfma_f32_16x16x32_bf16 v[16:19], v[136:139], v[188:191], v[16:19]
	v_mfma_f32_16x16x32_bf16 v[60:63], v[132:135], v[148:151], v[60:63]
	v_mfma_f32_16x16x32_bf16 v[56:59], v[140:143], v[148:151], v[56:59]
	v_mfma_f32_16x16x32_bf16 v[52:55], v[132:135], v[156:159], v[52:55]
	v_mfma_f32_16x16x32_bf16 v[48:51], v[140:143], v[156:159], v[48:51]
	v_mfma_f32_16x16x32_bf16 v[36:39], v[132:135], v[184:187], v[36:39]
	v_mfma_f32_16x16x32_bf16 v[32:35], v[140:143], v[184:187], v[32:35]
	v_mfma_f32_16x16x32_bf16 v[20:23], v[132:135], v[192:195], v[20:23]
	v_mfma_f32_16x16x32_bf16 v[16:19], v[140:143], v[192:195], v[16:19]
	s_setprio 0
	s_barrier
	s_add_u32 s2, s2, 0x40080
	s_addc_u32 s3, s3, 0
	s_add_i32 s8, s8, s54
	v_lshl_add_u64 v[128:129], s[2:3], 0, v[160:161]
	s_mov_b32 m0, s8
	s_nop 0
	global_load_lds_dwordx4 v[128:129], off
	v_lshl_add_u64 v[128:129], s[2:3], 0, v[162:163]
	s_add_i32 m0, s8, 0x2000
	s_nop 0
	global_load_lds_dwordx4 v[128:129], off
	s_waitcnt vmcnt(6)
	s_barrier
	s_setprio 1
	v_mfma_f32_16x16x32_bf16 v[44:47], v[196:199], v[144:147], v[44:47]
	v_mfma_f32_16x16x32_bf16 v[40:43], v[210:213], v[144:147], v[40:43]
	v_mfma_f32_16x16x32_bf16 v[28:31], v[196:199], v[152:155], v[28:31]
	v_mfma_f32_16x16x32_bf16 v[24:27], v[210:213], v[152:155], v[24:27]
	v_mfma_f32_16x16x32_bf16 v[12:15], v[196:199], v[180:183], v[12:15]
	v_mfma_f32_16x16x32_bf16 v[8:11], v[210:213], v[180:183], v[8:11]
	v_mfma_f32_16x16x32_bf16 v[4:7], v[196:199], v[188:191], v[4:7]
	v_mfma_f32_16x16x32_bf16 v[0:3], v[210:213], v[188:191], v[0:3]
	v_mfma_f32_16x16x32_bf16 v[44:47], v[200:203], v[148:151], v[44:47]
	v_mfma_f32_16x16x32_bf16 v[40:43], v[214:217], v[148:151], v[40:43]
	v_mfma_f32_16x16x32_bf16 v[28:31], v[200:203], v[156:159], v[28:31]
	v_mfma_f32_16x16x32_bf16 v[24:27], v[214:217], v[156:159], v[24:27]
	v_mfma_f32_16x16x32_bf16 v[12:15], v[200:203], v[184:187], v[12:15]
	v_mfma_f32_16x16x32_bf16 v[8:11], v[214:217], v[184:187], v[8:11]
	v_mfma_f32_16x16x32_bf16 v[4:7], v[200:203], v[192:195], v[4:7]
	v_mfma_f32_16x16x32_bf16 v[0:3], v[214:217], v[192:195], v[0:3]
	s_setprio 0
	s_add_i32 s41, s41, 2
	s_add_u32 s6, s6, 0x100
	s_addc_u32 s7, s7, 0
	s_add_u32 s39, s39, 0x100
	s_addc_u32 s40, s40, 0
	s_cmp_gt_u32 s41, 13
	s_barrier

.Ltr_LBB0_1245:
	s_branch .LBB0_1245

.LBB0_595:
	v_and_b32_e32 v149, 3, v125
	v_and_b32_e32 v150, 0x700, v125
	v_lshl_or_b32 v150, v149, 6, v150
	v_bfe_u32 v151, v125, 2, 6
	v_or_b32_e32 v150, v150, v151
	v_and_b32_e32 v152, 0xfe0, v125
	v_lshl_or_b32 v152, v149, 3, v152
	v_bfe_u32 v151, v125, 2, 3
	v_or_b32_e32 v152, v152, v151
	v_mov_b32_e32 v153, 0x800
	v_cmp_lt_i32_e32 vcc, v125, v153
	s_nop 1
	v_cndmask_b32_e32 v148, v152, v150, vcc
	s_movk_i32 s0, 0x7ff
	v_cmp_lt_i32_e64 s[70:71], s0, v125
	s_movk_i32 s0, 0x800
	v_cmp_gt_i32_e32 vcc, s0, v125
	v_lshlrev_b32_e32 v4, 5, v148
	v_lshrrev_b32_e32 v3, 2, v148
	s_and_saveexec_b64 s[0:1], vcc
	s_xor_b64 s[0:1], exec, s[0:1]
	s_cbranch_execz .LBB0_597
	v_ashrrev_i32_e32 v36, 9, v148
	v_and_b32_e32 v1, 0x7e0, v4
	v_lshlrev_b32_e32 v4, 7, v36
	v_and_or_b32 v4, v3, 64, v4
	v_sub_u32_e32 v3, 0x80, v1
	s_movk_i32 s2, 0x80
	v_ashrrev_i32_e32 v3, 5, v3
	v_cmp_gt_u32_e32 vcc, s2, v1
	v_ashrrev_i32_e32 v5, 31, v4
	v_lshl_or_b32 v2, v36, 11, v1
	v_cndmask_b32_e32 v144, 0, v3, vcc
	v_sub_u32_e32 v3, 0x860, v1
	v_lshrrev_b32_e32 v3, 5, v3
	v_min_u32_e32 v3, 8, v3
	v_lshlrev_b64 v[4:5], 12, v[4:5]
	v_sub_u32_e32 v3, v3, v144
	v_lshrrev_b32_e32 v0, 6, v148
	v_add_u32_e32 v2, 0x1000, v2
	v_lshl_add_u64 v[130:131], s[76:77], 0, v[4:5]
	v_lshl_add_u64 v[132:133], s[84:85], 0, v[4:5]
	v_add_u32_e32 v127, 1, v3
.LBB0_597:
	s_andn2_saveexec_b64 s[0:1], s[0:1]
	s_cbranch_execz .LBB0_599
	v_add_u32_e32 v0, 0xfffff800, v148
	v_lshrrev_b32_e32 v36, 6, v0
	v_and_b32_e32 v3, 8, v3
	v_lshl_or_b32 v168, v36, 4, v3
	v_readlane_b32 s2, v254, 62
	v_and_b32_e32 v1, 0xe0, v4
	v_lshlrev_b64 v[4:5], 12, v[168:169]
	v_readlane_b32 s3, v254, 63
	v_lshrrev_b32_e32 v0, 3, v148
	v_mov_b32_e32 v127, 8
	v_lshl_add_u64 v[130:131], s[2:3], 0, v[4:5]
	v_readlane_b32 s2, v255, 0
	v_readlane_b32 s3, v255, 1
	v_lshl_or_b32 v2, v36, 8, v1
	v_mov_b32_e32 v144, 0
	v_lshl_add_u64 v[132:133], s[2:3], 0, v[4:5]

.LBB0_677:
	s_ashr_i32 s23, s22, 31
	v_cmp_lt_i64_e32 vcc, s[24:25], v[174:175]
	s_lshl_b64 s[24:25], s[22:23], 19
	s_add_u32 s24, s36, s24
	s_addc_u32 s25, s37, s25
	s_and_b64 s[26:27], vcc, exec
	s_cselect_b32 s1, s25, s9
	s_cselect_b32 s7, s24, s8
	s_ashr_i32 s21, s20, 31
	s_lshl_b64 s[26:27], s[20:21], 19
	s_add_u32 s26, s38, s26
	s_addc_u32 s27, s39, s27
	s_and_b64 s[28:29], vcc, exec
	s_cselect_b32 s21, s27, s3
	s_cselect_b32 s23, s26, s2
	s_add_u32 s8, s8, 0x40080
	s_addc_u32 s9, s9, 0
	s_add_u32 s56, s2, 0x100
	s_addc_u32 s57, s3, 0
	s_mov_b32 s58, -2
	s_add_u32 s2, s8, 0xfffc0080
	s_addc_u32 s3, s9, -1
	s_add_i32 s59, 0, 0x10000
	v_add_u32_e32 v68, s59, v206
	ds_read_b128 v[48:51], v68
	ds_read_b128 v[52:55], v68 offset:1024
	ds_read_b128 v[60:63], v68 offset:2048
	ds_read_b128 v[68:71], v68 offset:3072
	s_cmp_eq_u32 s58, 12
	s_cselect_b32 s29, s1, s3
	s_cselect_b32 s28, s7, s2
	s_cselect_b32 s3, s21, s57
	s_cselect_b32 s2, s23, s56
	v_lshl_add_u64 v[200:201], s[8:9], 0, v[188:189]
	s_add_i32 m0, s41, 0xc000
	ds_read_b128 v[72:75], v207
	ds_read_b128 v[76:79], v207 offset:1024
	ds_read_b128 v[80:83], v207 offset:2048
	ds_read_b128 v[84:87], v207 offset:3072
	ds_read_b128 v[160:163], v207 offset:4096
	ds_read_b128 v[164:167], v207 offset:5120
	ds_read_b128 v[192:195], v207 offset:6144
	ds_read_b128 v[196:199], v207 offset:7168
	global_load_lds_dwordx4 v[200:201], off
	v_lshl_add_u64 v[200:201], s[8:9], 0, v[190:191]
	s_add_i32 m0, s41, 0xe000
	s_nop 0
	global_load_lds_dwordx4 v[200:201], off
	s_waitcnt lgkmcnt(8)
	s_barrier
	s_waitcnt lgkmcnt(0)
	s_setprio 1
	s_waitcnt lgkmcnt(0)
	v_mfma_f32_16x16x32_bf16 v[156:159], v[48:51], v[72:75], 0
	v_mfma_f32_16x16x32_bf16 v[152:155], v[60:63], v[72:75], 0
	v_mfma_f32_16x16x32_bf16 v[140:143], v[48:51], v[80:83], 0
	v_mfma_f32_16x16x32_bf16 v[136:139], v[60:63], v[80:83], 0
	v_mfma_f32_16x16x32_bf16 v[124:127], v[48:51], v[160:163], 0
	v_mfma_f32_16x16x32_bf16 v[120:123], v[60:63], v[160:163], 0
	v_mfma_f32_16x16x32_bf16 v[108:111], v[48:51], v[192:195], 0
	v_mfma_f32_16x16x32_bf16 v[104:107], v[60:63], v[192:195], 0
	v_mfma_f32_16x16x32_bf16 v[156:159], v[52:55], v[76:79], v[156:159]
	v_mfma_f32_16x16x32_bf16 v[152:155], v[68:71], v[76:79], v[152:155]
	v_mfma_f32_16x16x32_bf16 v[140:143], v[52:55], v[84:87], v[140:143]
	v_mfma_f32_16x16x32_bf16 v[136:139], v[68:71], v[84:87], v[136:139]
	v_mfma_f32_16x16x32_bf16 v[124:127], v[52:55], v[164:167], v[124:127]
	v_mfma_f32_16x16x32_bf16 v[120:123], v[68:71], v[164:167], v[120:123]
	v_mfma_f32_16x16x32_bf16 v[108:111], v[52:55], v[196:199], v[108:111]
	v_mfma_f32_16x16x32_bf16 v[104:107], v[68:71], v[196:199], v[104:107]
	s_setprio 0
	s_barrier
	s_add_i32 s62, 0, 0x14000
	s_add_i32 s59, s59, s40
	v_add_u32_e32 v168, s62, v206
	v_lshl_add_u64 v[240:241], s[2:3], 0, v[182:183]
	s_mov_b32 m0, s59
	ds_read_b128 v[200:203], v168
	ds_read_b128 v[208:211], v168 offset:1024
	ds_read_b128 v[212:215], v168 offset:2048
	ds_read_b128 v[216:219], v168 offset:3072
	global_load_lds_dwordx4 v[240:241], off
	v_lshl_add_u64 v[242:243], s[2:3], 0, v[186:187]
	s_add_i32 m0, s59, 0x2000
	s_nop 0
	global_load_lds_dwordx4 v[242:243], off
	s_barrier
	s_waitcnt lgkmcnt(0)
	s_setprio 1
	s_waitcnt lgkmcnt(0)
	v_mfma_f32_16x16x32_bf16 v[148:151], v[200:203], v[72:75], 0
	v_mfma_f32_16x16x32_bf16 v[72:75], v[212:215], v[72:75], 0
	v_mfma_f32_16x16x32_bf16 v[148:151], v[208:211], v[76:79], v[148:151]
	v_mfma_f32_16x16x32_bf16 v[72:75], v[216:219], v[76:79], v[72:75]
	v_mfma_f32_16x16x32_bf16 v[76:79], v[200:203], v[80:83], 0
	v_mfma_f32_16x16x32_bf16 v[80:83], v[212:215], v[80:83], 0
	v_mfma_f32_16x16x32_bf16 v[112:115], v[212:215], v[160:163], 0
	v_mfma_f32_16x16x32_bf16 v[100:103], v[200:203], v[192:195], 0
	v_mfma_f32_16x16x32_bf16 v[96:99], v[212:215], v[192:195], 0
	v_mfma_f32_16x16x32_bf16 v[76:79], v[208:211], v[84:87], v[76:79]
	v_mfma_f32_16x16x32_bf16 v[80:83], v[216:219], v[84:87], v[80:83]
	v_mfma_f32_16x16x32_bf16 v[84:87], v[200:203], v[160:163], 0
	v_mfma_f32_16x16x32_bf16 v[112:115], v[216:219], v[164:167], v[112:115]
	v_mfma_f32_16x16x32_bf16 v[100:103], v[208:211], v[196:199], v[100:103]
	v_mfma_f32_16x16x32_bf16 v[96:99], v[216:219], v[196:199], v[96:99]
	v_mfma_f32_16x16x32_bf16 v[84:87], v[208:211], v[164:167], v[84:87]
	s_setprio 0
	s_mov_b32 m0, s41
	v_lshl_add_u64 v[244:245], s[28:29], 0, v[180:181]
	s_barrier
	ds_read_b128 v[116:119], v207 offset:16384
	ds_read_b128 v[128:131], v207 offset:17408
	ds_read_b128 v[132:135], v207 offset:18432
	ds_read_b128 v[144:147], v207 offset:19456
	ds_read_b128 v[160:163], v207 offset:20480
	ds_read_b128 v[164:167], v207 offset:21504
	ds_read_b128 v[192:195], v207 offset:22528
	ds_read_b128 v[196:199], v207 offset:23552
	global_load_lds_dwordx4 v[244:245], off
	v_lshl_add_u64 v[246:247], s[28:29], 0, v[184:185]
	s_mov_b32 m0, s42
	s_nop 0
	global_load_lds_dwordx4 v[246:247], off
	s_barrier
	s_waitcnt lgkmcnt(0)
	s_setprio 1
	s_waitcnt lgkmcnt(0)
	v_mfma_f32_16x16x32_bf16 v[92:95], v[48:51], v[116:119], 0
	v_mfma_f32_16x16x32_bf16 v[88:91], v[60:63], v[116:119], 0
	v_mfma_f32_16x16x32_bf16 v[44:47], v[48:51], v[132:135], 0
	v_mfma_f32_16x16x32_bf16 v[40:43], v[60:63], v[132:135], 0
	v_mfma_f32_16x16x32_bf16 v[28:31], v[48:51], v[160:163], 0
	v_mfma_f32_16x16x32_bf16 v[24:27], v[60:63], v[160:163], 0
	v_mfma_f32_16x16x32_bf16 v[12:15], v[48:51], v[192:195], 0
	v_mfma_f32_16x16x32_bf16 v[8:11], v[60:63], v[192:195], 0
	v_mfma_f32_16x16x32_bf16 v[92:95], v[52:55], v[128:131], v[92:95]
	v_mfma_f32_16x16x32_bf16 v[88:91], v[68:71], v[128:131], v[88:91]
	v_mfma_f32_16x16x32_bf16 v[44:47], v[52:55], v[144:147], v[44:47]
	v_mfma_f32_16x16x32_bf16 v[40:43], v[68:71], v[144:147], v[40:43]
	v_mfma_f32_16x16x32_bf16 v[28:31], v[52:55], v[164:167], v[28:31]
	v_mfma_f32_16x16x32_bf16 v[24:27], v[68:71], v[164:167], v[24:27]
	v_mfma_f32_16x16x32_bf16 v[12:15], v[52:55], v[196:199], v[12:15]
	v_mfma_f32_16x16x32_bf16 v[8:11], v[68:71], v[196:199], v[8:11]
	s_setprio 0
	s_barrier
	s_add_u32 s60, s2, 0x40000
	s_addc_u32 s61, s3, 0
	s_add_i32 s59, s62, s40
	v_lshl_add_u64 v[48:49], s[60:61], 0, v[182:183]
	s_mov_b32 m0, s59
	s_nop 0
	global_load_lds_dwordx4 v[48:49], off
	v_lshl_add_u64 v[48:49], s[60:61], 0, v[186:187]
	s_add_i32 m0, s59, 0x2000
	s_nop 0
	global_load_lds_dwordx4 v[48:49], off
	s_waitcnt vmcnt(6)
	s_barrier
	s_setprio 1
	v_mfma_f32_16x16x32_bf16 v[36:39], v[200:203], v[132:135], 0
	v_mfma_f32_16x16x32_bf16 v[32:35], v[212:215], v[132:135], 0
	v_mfma_f32_16x16x32_bf16 v[20:23], v[200:203], v[160:163], 0
	v_mfma_f32_16x16x32_bf16 v[16:19], v[212:215], v[160:163], 0
	v_mfma_f32_16x16x32_bf16 v[4:7], v[200:203], v[192:195], 0
	v_mfma_f32_16x16x32_bf16 v[0:3], v[212:215], v[192:195], 0
	v_mfma_f32_16x16x32_bf16 v[48:51], v[200:203], v[116:119], 0
	v_mfma_f32_16x16x32_bf16 v[52:55], v[212:215], v[116:119], 0
	v_mfma_f32_16x16x32_bf16 v[36:39], v[208:211], v[144:147], v[36:39]
	v_mfma_f32_16x16x32_bf16 v[32:35], v[216:219], v[144:147], v[32:35]
	v_mfma_f32_16x16x32_bf16 v[20:23], v[208:211], v[164:167], v[20:23]
	v_mfma_f32_16x16x32_bf16 v[16:19], v[216:219], v[164:167], v[16:19]
	v_mfma_f32_16x16x32_bf16 v[4:7], v[208:211], v[196:199], v[4:7]
	v_mfma_f32_16x16x32_bf16 v[0:3], v[216:219], v[196:199], v[0:3]
	v_mfma_f32_16x16x32_bf16 v[48:51], v[208:211], v[128:131], v[48:51]
	v_mfma_f32_16x16x32_bf16 v[52:55], v[216:219], v[128:131], v[52:55]
	s_setprio 0
	s_add_i32 s59, 0, 0x18000
	v_add_u32_e32 v68, s59, v206
	s_barrier
	ds_read_b128 v[56:59], v68
	ds_read_b128 v[60:63], v68 offset:1024
	ds_read_b128 v[64:67], v68 offset:2048
	ds_read_b128 v[68:71], v68 offset:3072
	s_add_u32 s28, s28, 0x40000
	s_addc_u32 s29, s29, 0
	s_mov_b32 m0, s43
	v_lshl_add_u64 v[132:133], s[28:29], 0, v[180:181]
	ds_read_b128 v[116:119], v207 offset:32768
	ds_read_b128 v[128:131], v207 offset:33792
	ds_read_b128 v[160:163], v207 offset:34816
	ds_read_b128 v[164:167], v207 offset:35840
	ds_read_b128 v[192:195], v207 offset:36864
	ds_read_b128 v[196:199], v207 offset:37888
	ds_read_b128 v[200:203], v207 offset:38912
	ds_read_b128 v[208:211], v207 offset:39936
	global_load_lds_dwordx4 v[132:133], off
	v_lshl_add_u64 v[132:133], s[28:29], 0, v[184:185]
	s_mov_b32 m0, s44
	s_nop 0
	global_load_lds_dwordx4 v[132:133], off
	s_waitcnt lgkmcnt(8)
	s_barrier
	s_waitcnt lgkmcnt(0)
	s_setprio 1
	s_waitcnt lgkmcnt(0)
	v_mfma_f32_16x16x32_bf16 v[132:135], v[56:59], v[116:119], v[156:159]
	v_mfma_f32_16x16x32_bf16 v[156:159], v[60:63], v[128:131], v[132:135]
	v_mfma_f32_16x16x32_bf16 v[132:135], v[64:67], v[116:119], v[152:155]
	v_mfma_f32_16x16x32_bf16 v[152:155], v[68:71], v[128:131], v[132:135]
	v_mfma_f32_16x16x32_bf16 v[132:135], v[56:59], v[160:163], v[140:143]
	v_mfma_f32_16x16x32_bf16 v[140:143], v[60:63], v[164:167], v[132:135]
	v_mfma_f32_16x16x32_bf16 v[132:135], v[64:67], v[160:163], v[136:139]
	v_mfma_f32_16x16x32_bf16 v[124:127], v[56:59], v[192:195], v[124:127]
	v_mfma_f32_16x16x32_bf16 v[120:123], v[64:67], v[192:195], v[120:123]
	v_mfma_f32_16x16x32_bf16 v[108:111], v[56:59], v[200:203], v[108:111]
	v_mfma_f32_16x16x32_bf16 v[104:107], v[64:67], v[200:203], v[104:107]
	v_mfma_f32_16x16x32_bf16 v[136:139], v[68:71], v[164:167], v[132:135]
	v_mfma_f32_16x16x32_bf16 v[124:127], v[60:63], v[196:199], v[124:127]
	v_mfma_f32_16x16x32_bf16 v[120:123], v[68:71], v[196:199], v[120:123]
	v_mfma_f32_16x16x32_bf16 v[108:111], v[60:63], v[208:211], v[108:111]
	v_mfma_f32_16x16x32_bf16 v[104:107], v[68:71], v[208:211], v[104:107]
	s_setprio 0
	s_barrier
	s_add_i32 s28, 0, 0x1c000
	v_add_u32_e32 v132, s28, v206
	s_add_i32 s29, s59, s40
	ds_read_b128 v[212:215], v132
	ds_read_b128 v[216:219], v132 offset:1024
	ds_read_b128 v[220:223], v132 offset:2048
	ds_read_b128 v[236:239], v132 offset:3072
	v_lshl_add_u64 v[132:133], v[240:241], 0, s[78:79]
	s_mov_b32 m0, s29
	s_nop 0
	global_load_lds_dwordx4 v[132:133], off
	v_lshl_add_u64 v[132:133], v[242:243], 0, s[78:79]
	s_add_i32 m0, s29, 0x2000
	s_nop 0
	global_load_lds_dwordx4 v[132:133], off
	s_barrier
	s_waitcnt lgkmcnt(0)
	s_setprio 1
	s_waitcnt lgkmcnt(0)
	v_mfma_f32_16x16x32_bf16 v[72:75], v[220:223], v[116:119], v[72:75]
	v_mfma_f32_16x16x32_bf16 v[132:135], v[212:215], v[116:119], v[148:151]
	v_mfma_f32_16x16x32_bf16 v[144:147], v[236:239], v[128:131], v[72:75]
	v_mfma_f32_16x16x32_bf16 v[72:75], v[212:215], v[160:163], v[76:79]
	v_mfma_f32_16x16x32_bf16 v[148:151], v[216:219], v[128:131], v[132:135]
	v_mfma_f32_16x16x32_bf16 v[132:135], v[216:219], v[164:167], v[72:75]
	v_mfma_f32_16x16x32_bf16 v[72:75], v[220:223], v[160:163], v[80:83]
	v_mfma_f32_16x16x32_bf16 v[128:131], v[236:239], v[164:167], v[72:75]
	v_mfma_f32_16x16x32_bf16 v[72:75], v[212:215], v[192:195], v[84:87]
	v_mfma_f32_16x16x32_bf16 v[116:119], v[216:219], v[196:199], v[72:75]
	v_mfma_f32_16x16x32_bf16 v[72:75], v[220:223], v[192:195], v[112:115]
	v_mfma_f32_16x16x32_bf16 v[112:115], v[236:239], v[196:199], v[72:75]
	v_mfma_f32_16x16x32_bf16 v[72:75], v[212:215], v[200:203], v[100:103]
	v_mfma_f32_16x16x32_bf16 v[100:103], v[216:219], v[208:211], v[72:75]
	v_mfma_f32_16x16x32_bf16 v[72:75], v[220:223], v[200:203], v[96:99]
	v_mfma_f32_16x16x32_bf16 v[96:99], v[236:239], v[208:211], v[72:75]
	s_setprio 0
	s_mov_b32 m0, s53
	v_lshl_add_u64 v[200:201], v[244:245], 0, s[78:79]
	s_barrier
	s_nop 2
	ds_read_b128 v[72:75], v207 offset:49152
	ds_read_b128 v[76:79], v207 offset:50176
	ds_read_b128 v[80:83], v207 offset:51200
	ds_read_b128 v[84:87], v207 offset:52224
	ds_read_b128 v[160:163], v207 offset:53248
	ds_read_b128 v[164:167], v207 offset:54272
	ds_read_b128 v[192:195], v207 offset:55296
	ds_read_b128 v[196:199], v207 offset:56320
	global_load_lds_dwordx4 v[200:201], off
	v_lshl_add_u64 v[200:201], v[246:247], 0, s[78:79]
	s_mov_b32 m0, s54
	s_nop 0
	global_load_lds_dwordx4 v[200:201], off
	s_barrier
	s_waitcnt lgkmcnt(0)
	s_setprio 1
	s_waitcnt lgkmcnt(0)
	v_mfma_f32_16x16x32_bf16 v[92:95], v[56:59], v[72:75], v[92:95]
	v_mfma_f32_16x16x32_bf16 v[88:91], v[64:67], v[72:75], v[88:91]
	v_mfma_f32_16x16x32_bf16 v[44:47], v[56:59], v[80:83], v[44:47]
	v_mfma_f32_16x16x32_bf16 v[40:43], v[64:67], v[80:83], v[40:43]
	v_mfma_f32_16x16x32_bf16 v[28:31], v[56:59], v[160:163], v[28:31]
	v_mfma_f32_16x16x32_bf16 v[24:27], v[64:67], v[160:163], v[24:27]
	v_mfma_f32_16x16x32_bf16 v[12:15], v[56:59], v[192:195], v[12:15]
	v_mfma_f32_16x16x32_bf16 v[8:11], v[64:67], v[192:195], v[8:11]
	v_mfma_f32_16x16x32_bf16 v[92:95], v[60:63], v[76:79], v[92:95]
	v_mfma_f32_16x16x32_bf16 v[88:91], v[68:71], v[76:79], v[88:91]
	v_mfma_f32_16x16x32_bf16 v[44:47], v[60:63], v[84:87], v[44:47]
	v_mfma_f32_16x16x32_bf16 v[40:43], v[68:71], v[84:87], v[40:43]
	v_mfma_f32_16x16x32_bf16 v[28:31], v[60:63], v[164:167], v[28:31]
	v_mfma_f32_16x16x32_bf16 v[24:27], v[68:71], v[164:167], v[24:27]
	v_mfma_f32_16x16x32_bf16 v[12:15], v[60:63], v[196:199], v[12:15]
	v_mfma_f32_16x16x32_bf16 v[8:11], v[68:71], v[196:199], v[8:11]
	s_setprio 0
	s_barrier
	s_add_u32 s2, s2, 0x40080
	s_addc_u32 s3, s3, 0
	s_add_i32 s28, s28, s40
	v_lshl_add_u64 v[56:57], s[2:3], 0, v[182:183]
	s_mov_b32 m0, s28
	s_nop 0
	global_load_lds_dwordx4 v[56:57], off
	v_lshl_add_u64 v[56:57], s[2:3], 0, v[186:187]
	s_add_i32 m0, s28, 0x2000
	s_nop 0
	global_load_lds_dwordx4 v[56:57], off
	s_waitcnt vmcnt(6)
	s_barrier
	s_setprio 1
	v_mfma_f32_16x16x32_bf16 v[48:51], v[212:215], v[72:75], v[48:51]
	v_mfma_f32_16x16x32_bf16 v[64:67], v[216:219], v[76:79], v[48:51]
	v_mfma_f32_16x16x32_bf16 v[48:51], v[220:223], v[72:75], v[52:55]
	v_mfma_f32_16x16x32_bf16 v[36:39], v[212:215], v[80:83], v[36:39]
	v_mfma_f32_16x16x32_bf16 v[32:35], v[220:223], v[80:83], v[32:35]
	v_mfma_f32_16x16x32_bf16 v[20:23], v[212:215], v[160:163], v[20:23]
	v_mfma_f32_16x16x32_bf16 v[16:19], v[220:223], v[160:163], v[16:19]
	v_mfma_f32_16x16x32_bf16 v[4:7], v[212:215], v[192:195], v[4:7]
	v_mfma_f32_16x16x32_bf16 v[0:3], v[220:223], v[192:195], v[0:3]
	v_mfma_f32_16x16x32_bf16 v[56:59], v[236:239], v[76:79], v[48:51]
	v_mfma_f32_16x16x32_bf16 v[36:39], v[216:219], v[84:87], v[36:39]
	v_mfma_f32_16x16x32_bf16 v[32:35], v[236:239], v[84:87], v[32:35]
	v_mfma_f32_16x16x32_bf16 v[20:23], v[216:219], v[164:167], v[20:23]
	v_mfma_f32_16x16x32_bf16 v[16:19], v[236:239], v[164:167], v[16:19]
	v_mfma_f32_16x16x32_bf16 v[4:7], v[216:219], v[196:199], v[4:7]
	v_mfma_f32_16x16x32_bf16 v[0:3], v[236:239], v[196:199], v[0:3]
	s_setprio 0
	s_add_i32 s58, s58, 2
	s_add_u32 s8, s8, 0x100
	s_addc_u32 s9, s9, 0
	s_add_u32 s56, s56, 0x100
	s_addc_u32 s57, s57, 0
	s_cmp_gt_u32 s58, 13
	s_barrier

.LBB0_879:
	s_ashr_i32 s39, s38, 31
	v_cmp_lt_i64_e32 vcc, s[12:13], v[178:179]
	s_lshl_b64 s[12:13], s[38:39], 19
	s_add_u32 s40, s49, s12
	s_addc_u32 s41, s50, s13
	s_and_b64 s[12:13], vcc, exec
	s_cselect_b32 s1, s41, s11
	s_cselect_b32 s9, s40, s10
	s_ashr_i32 s37, s36, 31
	s_lshl_b64 s[12:13], s[36:37], 19
	s_add_u32 s42, s51, s12
	s_addc_u32 s43, s52, s13
	s_and_b64 s[12:13], vcc, exec
	s_cselect_b32 s14, s43, s3
	s_cselect_b32 s15, s42, s2
	s_add_u32 s10, s10, 0x40080
	s_addc_u32 s11, s11, 0
	s_add_u32 s37, s2, 0x100
	s_addc_u32 s39, s3, 0
	s_mov_b32 s67, -2
	s_add_u32 s2, s10, 0xfffc0080
	s_addc_u32 s3, s11, -1
	s_add_i32 s68, 0, 0x10000
	v_add_u32_e32 v108, s68, v237
	ds_read_b128 v[48:51], v108
	ds_read_b128 v[52:55], v108 offset:1024
	ds_read_b128 v[104:107], v108 offset:2048
	ds_read_b128 v[108:111], v108 offset:3072
	s_cmp_eq_u32 s67, 12
	s_cselect_b32 s13, s1, s3
	s_cselect_b32 s12, s9, s2
	s_cselect_b32 s3, s14, s39
	s_cselect_b32 s2, s15, s37
	v_lshl_add_u64 v[198:199], s[10:11], 0, v[186:187]
	s_add_i32 m0, s54, 0xc000
	ds_read_b128 v[112:115], v238
	ds_read_b128 v[116:119], v238 offset:1024
	ds_read_b128 v[120:123], v238 offset:2048
	ds_read_b128 v[156:159], v238 offset:3072
	ds_read_b128 v[160:163], v238 offset:4096
	ds_read_b128 v[164:167], v238 offset:5120
	ds_read_b128 v[190:193], v238 offset:6144
	ds_read_b128 v[194:197], v238 offset:7168
	global_load_lds_dwordx4 v[198:199], off
	v_lshl_add_u64 v[198:199], s[10:11], 0, v[188:189]
	s_add_i32 m0, s54, 0xe000
	s_nop 0
	global_load_lds_dwordx4 v[198:199], off
	s_waitcnt lgkmcnt(8)
	s_barrier
	s_waitcnt lgkmcnt(0)
	s_setprio 1
	s_waitcnt lgkmcnt(0)
	v_mfma_f32_16x16x32_bf16 v[152:155], v[48:51], v[112:115], 0
	v_mfma_f32_16x16x32_bf16 v[68:71], v[104:107], v[112:115], 0
	v_mfma_f32_16x16x32_bf16 v[148:151], v[48:51], v[120:123], 0
	v_mfma_f32_16x16x32_bf16 v[64:67], v[104:107], v[120:123], 0
	v_mfma_f32_16x16x32_bf16 v[136:139], v[48:51], v[160:163], 0
	v_mfma_f32_16x16x32_bf16 v[44:47], v[104:107], v[160:163], 0
	v_mfma_f32_16x16x32_bf16 v[128:131], v[48:51], v[190:193], 0
	v_mfma_f32_16x16x32_bf16 v[40:43], v[104:107], v[190:193], 0
	v_mfma_f32_16x16x32_bf16 v[152:155], v[52:55], v[116:119], v[152:155]
	v_mfma_f32_16x16x32_bf16 v[68:71], v[108:111], v[116:119], v[68:71]
	v_mfma_f32_16x16x32_bf16 v[148:151], v[52:55], v[156:159], v[148:151]
	v_mfma_f32_16x16x32_bf16 v[64:67], v[108:111], v[156:159], v[64:67]
	v_mfma_f32_16x16x32_bf16 v[136:139], v[52:55], v[164:167], v[136:139]
	v_mfma_f32_16x16x32_bf16 v[44:47], v[108:111], v[164:167], v[44:47]
	v_mfma_f32_16x16x32_bf16 v[128:131], v[52:55], v[194:197], v[128:131]
	v_mfma_f32_16x16x32_bf16 v[40:43], v[108:111], v[194:197], v[40:43]
	s_setprio 0
	s_barrier
	s_add_i32 s70, 0, 0x14000
	s_add_i32 s68, s68, s53
	v_add_u32_e32 v210, s70, v237
	v_lshl_add_u64 v[218:219], s[2:3], 0, v[168:169]
	s_mov_b32 m0, s68
	ds_read_b128 v[198:201], v210
	ds_read_b128 v[202:205], v210 offset:1024
	ds_read_b128 v[206:209], v210 offset:2048
	ds_read_b128 v[210:213], v210 offset:3072
	global_load_lds_dwordx4 v[218:219], off
	v_lshl_add_u64 v[220:221], s[2:3], 0, v[184:185]
	s_add_i32 m0, s68, 0x2000
	s_nop 0
	global_load_lds_dwordx4 v[220:221], off
	s_barrier
	s_waitcnt lgkmcnt(0)
	s_setprio 1
	s_waitcnt lgkmcnt(0)
	v_mfma_f32_16x16x32_bf16 v[144:147], v[198:201], v[112:115], 0
	v_mfma_f32_16x16x32_bf16 v[60:63], v[206:209], v[112:115], 0
	v_mfma_f32_16x16x32_bf16 v[56:59], v[206:209], v[120:123], 0
	v_mfma_f32_16x16x32_bf16 v[36:39], v[206:209], v[160:163], 0
	v_mfma_f32_16x16x32_bf16 v[32:35], v[206:209], v[190:193], 0
	v_mfma_f32_16x16x32_bf16 v[144:147], v[202:205], v[116:119], v[144:147]
	v_mfma_f32_16x16x32_bf16 v[60:63], v[210:213], v[116:119], v[60:63]
	v_mfma_f32_16x16x32_bf16 v[112:115], v[198:201], v[120:123], 0
	v_mfma_f32_16x16x32_bf16 v[56:59], v[210:213], v[156:159], v[56:59]
	v_mfma_f32_16x16x32_bf16 v[116:119], v[198:201], v[160:163], 0
	v_mfma_f32_16x16x32_bf16 v[36:39], v[210:213], v[164:167], v[36:39]
	v_mfma_f32_16x16x32_bf16 v[120:123], v[198:201], v[190:193], 0
	v_mfma_f32_16x16x32_bf16 v[32:35], v[210:213], v[194:197], v[32:35]
	v_mfma_f32_16x16x32_bf16 v[112:115], v[202:205], v[156:159], v[112:115]
	v_mfma_f32_16x16x32_bf16 v[116:119], v[202:205], v[164:167], v[116:119]
	v_mfma_f32_16x16x32_bf16 v[120:123], v[202:205], v[194:197], v[120:123]
	s_setprio 0
	s_mov_b32 m0, s54
	v_lshl_add_u64 v[222:223], s[12:13], 0, v[180:181]
	s_barrier
	ds_read_b128 v[124:127], v238 offset:16384
	ds_read_b128 v[132:135], v238 offset:17408
	ds_read_b128 v[140:143], v238 offset:18432
	ds_read_b128 v[156:159], v238 offset:19456
	ds_read_b128 v[160:163], v238 offset:20480
	ds_read_b128 v[164:167], v238 offset:21504
	ds_read_b128 v[190:193], v238 offset:22528
	ds_read_b128 v[194:197], v238 offset:23552
	global_load_lds_dwordx4 v[222:223], off
	v_lshl_add_u64 v[240:241], s[12:13], 0, v[182:183]
	s_mov_b32 m0, s55
	s_nop 0
	global_load_lds_dwordx4 v[240:241], off
	s_barrier
	s_waitcnt lgkmcnt(0)
	s_setprio 1
	s_waitcnt lgkmcnt(0)
	v_mfma_f32_16x16x32_bf16 v[100:103], v[48:51], v[124:127], 0
	v_mfma_f32_16x16x32_bf16 v[28:31], v[104:107], v[124:127], 0
	v_mfma_f32_16x16x32_bf16 v[96:99], v[48:51], v[140:143], 0
	v_mfma_f32_16x16x32_bf16 v[24:27], v[104:107], v[140:143], 0
	v_mfma_f32_16x16x32_bf16 v[84:87], v[48:51], v[160:163], 0
	v_mfma_f32_16x16x32_bf16 v[12:15], v[104:107], v[160:163], 0
	v_mfma_f32_16x16x32_bf16 v[8:11], v[104:107], v[190:193], 0
	v_mfma_f32_16x16x32_bf16 v[100:103], v[52:55], v[132:135], v[100:103]
	v_mfma_f32_16x16x32_bf16 v[28:31], v[108:111], v[132:135], v[28:31]
	v_mfma_f32_16x16x32_bf16 v[96:99], v[52:55], v[156:159], v[96:99]
	v_mfma_f32_16x16x32_bf16 v[24:27], v[108:111], v[156:159], v[24:27]
	v_mfma_f32_16x16x32_bf16 v[84:87], v[52:55], v[164:167], v[84:87]
	v_mfma_f32_16x16x32_bf16 v[12:15], v[108:111], v[164:167], v[12:15]
	v_mfma_f32_16x16x32_bf16 v[48:51], v[48:51], v[190:193], 0
	v_mfma_f32_16x16x32_bf16 v[8:11], v[108:111], v[194:197], v[8:11]
	v_mfma_f32_16x16x32_bf16 v[48:51], v[52:55], v[194:197], v[48:51]
	s_setprio 0
	s_barrier
	s_add_u32 s68, s2, 0x40000
	s_addc_u32 s69, s3, 0
	s_add_i32 s70, s70, s53
	v_lshl_add_u64 v[52:53], s[68:69], 0, v[168:169]
	s_mov_b32 m0, s70
	s_nop 0
	global_load_lds_dwordx4 v[52:53], off
	v_lshl_add_u64 v[52:53], s[68:69], 0, v[184:185]
	s_add_i32 m0, s70, 0x2000
	s_nop 0
	global_load_lds_dwordx4 v[52:53], off
	s_waitcnt vmcnt(6)
	s_barrier
	s_setprio 1
	v_mfma_f32_16x16x32_bf16 v[76:79], v[198:201], v[140:143], 0
	v_mfma_f32_16x16x32_bf16 v[20:23], v[206:209], v[124:127], 0
	v_mfma_f32_16x16x32_bf16 v[88:91], v[202:205], v[156:159], v[76:79]
	v_mfma_f32_16x16x32_bf16 v[16:19], v[206:209], v[140:143], 0
	v_mfma_f32_16x16x32_bf16 v[76:79], v[198:201], v[160:163], 0
	v_mfma_f32_16x16x32_bf16 v[4:7], v[206:209], v[160:163], 0
	v_mfma_f32_16x16x32_bf16 v[72:75], v[198:201], v[190:193], 0
	v_mfma_f32_16x16x32_bf16 v[0:3], v[206:209], v[190:193], 0
	v_mfma_f32_16x16x32_bf16 v[52:55], v[198:201], v[124:127], 0
	v_mfma_f32_16x16x32_bf16 v[20:23], v[210:213], v[132:135], v[20:23]
	v_mfma_f32_16x16x32_bf16 v[16:19], v[210:213], v[156:159], v[16:19]
	v_mfma_f32_16x16x32_bf16 v[80:83], v[202:205], v[164:167], v[76:79]
	v_mfma_f32_16x16x32_bf16 v[4:7], v[210:213], v[164:167], v[4:7]
	v_mfma_f32_16x16x32_bf16 v[72:75], v[202:205], v[194:197], v[72:75]
	v_mfma_f32_16x16x32_bf16 v[0:3], v[210:213], v[194:197], v[0:3]
	v_mfma_f32_16x16x32_bf16 v[52:55], v[202:205], v[132:135], v[52:55]
	s_setprio 0
	s_add_i32 s68, 0, 0x18000
	v_add_u32_e32 v108, s68, v237
	s_barrier
	ds_read_b128 v[76:79], v108
	ds_read_b128 v[92:95], v108 offset:1024
	ds_read_b128 v[104:107], v108 offset:2048
	ds_read_b128 v[108:111], v108 offset:3072
	s_add_u32 s12, s12, 0x40000
	s_addc_u32 s13, s13, 0
	s_mov_b32 m0, s56
	v_lshl_add_u64 v[140:141], s[12:13], 0, v[180:181]
	ds_read_b128 v[124:127], v238 offset:32768
	ds_read_b128 v[132:135], v238 offset:33792
	ds_read_b128 v[156:159], v238 offset:34816
	ds_read_b128 v[160:163], v238 offset:35840
	ds_read_b128 v[164:167], v238 offset:36864
	ds_read_b128 v[190:193], v238 offset:37888
	ds_read_b128 v[194:197], v238 offset:38912
	ds_read_b128 v[198:201], v238 offset:39936
	global_load_lds_dwordx4 v[140:141], off
	v_lshl_add_u64 v[140:141], s[12:13], 0, v[182:183]
	s_mov_b32 m0, s57
	s_nop 0
	global_load_lds_dwordx4 v[140:141], off
	s_waitcnt lgkmcnt(8)
	s_barrier
	s_waitcnt lgkmcnt(0)
	s_setprio 1
	s_waitcnt lgkmcnt(0)
	v_mfma_f32_16x16x32_bf16 v[140:143], v[76:79], v[124:127], v[152:155]
	v_mfma_f32_16x16x32_bf16 v[152:155], v[92:95], v[132:135], v[140:143]
	v_mfma_f32_16x16x32_bf16 v[68:71], v[104:107], v[124:127], v[68:71]
	v_mfma_f32_16x16x32_bf16 v[140:143], v[76:79], v[156:159], v[148:151]
	v_mfma_f32_16x16x32_bf16 v[64:67], v[104:107], v[156:159], v[64:67]
	v_mfma_f32_16x16x32_bf16 v[136:139], v[76:79], v[164:167], v[136:139]
	v_mfma_f32_16x16x32_bf16 v[44:47], v[104:107], v[164:167], v[44:47]
	v_mfma_f32_16x16x32_bf16 v[128:131], v[76:79], v[194:197], v[128:131]
	v_mfma_f32_16x16x32_bf16 v[40:43], v[104:107], v[194:197], v[40:43]
	v_mfma_f32_16x16x32_bf16 v[68:71], v[108:111], v[132:135], v[68:71]
	v_mfma_f32_16x16x32_bf16 v[148:151], v[92:95], v[160:163], v[140:143]
	v_mfma_f32_16x16x32_bf16 v[64:67], v[108:111], v[160:163], v[64:67]
	v_mfma_f32_16x16x32_bf16 v[136:139], v[92:95], v[190:193], v[136:139]
	v_mfma_f32_16x16x32_bf16 v[44:47], v[108:111], v[190:193], v[44:47]
	v_mfma_f32_16x16x32_bf16 v[128:131], v[92:95], v[198:201], v[128:131]
	v_mfma_f32_16x16x32_bf16 v[40:43], v[108:111], v[198:201], v[40:43]
	s_setprio 0
	s_barrier
	s_add_i32 s12, 0, 0x1c000
	v_add_u32_e32 v140, s12, v237
	s_add_i32 s13, s68, s53
	ds_read_b128 v[202:205], v140
	ds_read_b128 v[206:209], v140 offset:1024
	ds_read_b128 v[210:213], v140 offset:2048
	ds_read_b128 v[214:217], v140 offset:3072
	v_lshl_add_u64 v[140:141], v[218:219], 0, s[78:79]
	s_mov_b32 m0, s13
	s_nop 0
	global_load_lds_dwordx4 v[140:141], off
	v_lshl_add_u64 v[140:141], v[220:221], 0, s[78:79]
	s_add_i32 m0, s13, 0x2000
	s_nop 0
	global_load_lds_dwordx4 v[140:141], off
	s_barrier
	s_waitcnt lgkmcnt(0)
	s_setprio 1
	s_waitcnt lgkmcnt(0)
	v_mfma_f32_16x16x32_bf16 v[140:143], v[202:205], v[124:127], v[144:147]
	v_mfma_f32_16x16x32_bf16 v[112:115], v[202:205], v[156:159], v[112:115]
	v_mfma_f32_16x16x32_bf16 v[144:147], v[206:209], v[132:135], v[140:143]
	v_mfma_f32_16x16x32_bf16 v[60:63], v[210:213], v[124:127], v[60:63]
	v_mfma_f32_16x16x32_bf16 v[140:143], v[206:209], v[160:163], v[112:115]
	v_mfma_f32_16x16x32_bf16 v[112:115], v[202:205], v[164:167], v[116:119]
	v_mfma_f32_16x16x32_bf16 v[60:63], v[214:217], v[132:135], v[60:63]
	v_mfma_f32_16x16x32_bf16 v[56:59], v[210:213], v[156:159], v[56:59]
	v_mfma_f32_16x16x32_bf16 v[132:135], v[206:209], v[190:193], v[112:115]
	v_mfma_f32_16x16x32_bf16 v[36:39], v[210:213], v[164:167], v[36:39]
	v_mfma_f32_16x16x32_bf16 v[112:115], v[202:205], v[194:197], v[120:123]
	v_mfma_f32_16x16x32_bf16 v[32:35], v[210:213], v[194:197], v[32:35]
	v_mfma_f32_16x16x32_bf16 v[56:59], v[214:217], v[160:163], v[56:59]
	v_mfma_f32_16x16x32_bf16 v[36:39], v[214:217], v[190:193], v[36:39]
	v_mfma_f32_16x16x32_bf16 v[124:127], v[206:209], v[198:201], v[112:115]
	v_mfma_f32_16x16x32_bf16 v[32:35], v[214:217], v[198:201], v[32:35]
	s_setprio 0
	s_mov_b32 m0, s62
	v_lshl_add_u64 v[198:199], v[222:223], 0, s[78:79]
	s_barrier
	ds_read_b128 v[112:115], v238 offset:49152
	ds_read_b128 v[116:119], v238 offset:50176
	ds_read_b128 v[120:123], v238 offset:51200
	ds_read_b128 v[156:159], v238 offset:52224
	ds_read_b128 v[160:163], v238 offset:53248
	ds_read_b128 v[164:167], v238 offset:54272
	ds_read_b128 v[190:193], v238 offset:55296
	ds_read_b128 v[194:197], v238 offset:56320
	global_load_lds_dwordx4 v[198:199], off
	v_lshl_add_u64 v[198:199], v[240:241], 0, s[78:79]
	s_mov_b32 m0, s63
	s_nop 0
	global_load_lds_dwordx4 v[198:199], off
	s_barrier
	s_waitcnt lgkmcnt(0)
	s_setprio 1
	s_waitcnt lgkmcnt(0)
	v_mfma_f32_16x16x32_bf16 v[100:103], v[76:79], v[112:115], v[100:103]
	v_mfma_f32_16x16x32_bf16 v[28:31], v[104:107], v[112:115], v[28:31]
	v_mfma_f32_16x16x32_bf16 v[96:99], v[76:79], v[120:123], v[96:99]
	v_mfma_f32_16x16x32_bf16 v[24:27], v[104:107], v[120:123], v[24:27]
	v_mfma_f32_16x16x32_bf16 v[84:87], v[76:79], v[160:163], v[84:87]
	v_mfma_f32_16x16x32_bf16 v[12:15], v[104:107], v[160:163], v[12:15]
	v_mfma_f32_16x16x32_bf16 v[48:51], v[76:79], v[190:193], v[48:51]
	v_mfma_f32_16x16x32_bf16 v[8:11], v[104:107], v[190:193], v[8:11]
	v_mfma_f32_16x16x32_bf16 v[100:103], v[92:95], v[116:119], v[100:103]
	v_mfma_f32_16x16x32_bf16 v[28:31], v[108:111], v[116:119], v[28:31]
	v_mfma_f32_16x16x32_bf16 v[96:99], v[92:95], v[156:159], v[96:99]
	v_mfma_f32_16x16x32_bf16 v[24:27], v[108:111], v[156:159], v[24:27]
	v_mfma_f32_16x16x32_bf16 v[84:87], v[92:95], v[164:167], v[84:87]
	v_mfma_f32_16x16x32_bf16 v[12:15], v[108:111], v[164:167], v[12:15]
	v_mfma_f32_16x16x32_bf16 v[76:79], v[92:95], v[194:197], v[48:51]
	v_mfma_f32_16x16x32_bf16 v[8:11], v[108:111], v[194:197], v[8:11]
	s_setprio 0
	s_barrier
	s_add_u32 s2, s2, 0x40080
	s_addc_u32 s3, s3, 0
	s_add_i32 s12, s12, s53
	v_lshl_add_u64 v[48:49], s[2:3], 0, v[168:169]
	s_mov_b32 m0, s12
	s_nop 0
	global_load_lds_dwordx4 v[48:49], off
	v_lshl_add_u64 v[48:49], s[2:3], 0, v[184:185]
	s_add_i32 m0, s12, 0x2000
	s_nop 0
	global_load_lds_dwordx4 v[48:49], off
	s_waitcnt vmcnt(6)
	s_barrier
	s_setprio 1
	v_mfma_f32_16x16x32_bf16 v[48:51], v[202:205], v[112:115], v[52:55]
	v_mfma_f32_16x16x32_bf16 v[92:95], v[206:209], v[116:119], v[48:51]
	v_mfma_f32_16x16x32_bf16 v[48:51], v[202:205], v[120:123], v[88:91]
	v_mfma_f32_16x16x32_bf16 v[88:91], v[206:209], v[156:159], v[48:51]
	v_mfma_f32_16x16x32_bf16 v[48:51], v[202:205], v[160:163], v[80:83]
	v_mfma_f32_16x16x32_bf16 v[20:23], v[210:213], v[112:115], v[20:23]
	v_mfma_f32_16x16x32_bf16 v[16:19], v[210:213], v[120:123], v[16:19]
	v_mfma_f32_16x16x32_bf16 v[80:83], v[206:209], v[164:167], v[48:51]
	v_mfma_f32_16x16x32_bf16 v[4:7], v[210:213], v[160:163], v[4:7]
	v_mfma_f32_16x16x32_bf16 v[48:51], v[202:205], v[190:193], v[72:75]
	v_mfma_f32_16x16x32_bf16 v[0:3], v[210:213], v[190:193], v[0:3]
	v_mfma_f32_16x16x32_bf16 v[20:23], v[214:217], v[116:119], v[20:23]
	v_mfma_f32_16x16x32_bf16 v[16:19], v[214:217], v[156:159], v[16:19]
	v_mfma_f32_16x16x32_bf16 v[4:7], v[214:217], v[164:167], v[4:7]
	v_mfma_f32_16x16x32_bf16 v[72:75], v[206:209], v[194:197], v[48:51]
	v_mfma_f32_16x16x32_bf16 v[0:3], v[214:217], v[194:197], v[0:3]
	s_setprio 0
	s_add_i32 s67, s67, 2
	s_add_u32 s10, s10, 0x100
	s_addc_u32 s11, s11, 0
	s_add_u32 s37, s37, 0x100
	s_addc_u32 s39, s39, 0
	s_cmp_gt_u32 s67, 13
	s_barrier

.LBB0_1048:
	s_add_u32 s56, s2, 0x100
	s_addc_u32 s57, s3, 0
	s_mov_b32 s58, -2
	s_add_u32 s2, s24, 0x100
	s_addc_u32 s3, s25, 0
	s_add_i32 s59, 0, 0x10000
	v_add_u32_e32 v52, s59, v194
	ds_read_b128 v[40:43], v52
	ds_read_b128 v[44:47], v52 offset:1024
	ds_read_b128 v[48:51], v52 offset:2048
	ds_read_b128 v[52:55], v52 offset:3072
	s_cmp_eq_u32 s58, 40
	s_cselect_b32 s27, s1, s3
	s_cselect_b32 s26, s0, s2
	s_cselect_b32 s9, s23, s57
	s_cselect_b32 s8, s22, s56
	v_lshl_add_u64 v[190:191], s[24:25], 0, v[166:167]
	s_add_i32 m0, s37, 0xc000
	ds_read_b128 v[56:59], v195
	ds_read_b128 v[60:63], v195 offset:1024
	ds_read_b128 v[72:75], v195 offset:2048
	ds_read_b128 v[84:87], v195 offset:3072
	ds_read_b128 v[182:185], v195 offset:4096
	ds_read_b128 v[186:189], v195 offset:5120
	ds_read_b128 v[196:199], v195 offset:6144
	ds_read_b128 v[200:203], v195 offset:7168
	global_load_lds_dwordx4 v[190:191], off
	v_lshl_add_u64 v[190:191], s[24:25], 0, v[180:181]
	s_add_i32 m0, s37, 0xe000
	s_nop 0
	global_load_lds_dwordx4 v[190:191], off
	s_waitcnt lgkmcnt(8)
	s_barrier
	s_waitcnt lgkmcnt(0)
	s_setprio 1
	s_waitcnt lgkmcnt(0)
	v_mfma_f32_16x16x32_bf16 v[156:159], v[40:43], v[56:59], 0
	v_mfma_f32_16x16x32_bf16 v[152:155], v[48:51], v[56:59], 0
	v_mfma_f32_16x16x32_bf16 v[140:143], v[40:43], v[72:75], 0
	v_mfma_f32_16x16x32_bf16 v[136:139], v[48:51], v[72:75], 0
	v_mfma_f32_16x16x32_bf16 v[124:127], v[40:43], v[182:185], 0
	v_mfma_f32_16x16x32_bf16 v[120:123], v[48:51], v[182:185], 0
	v_mfma_f32_16x16x32_bf16 v[108:111], v[40:43], v[196:199], 0
	v_mfma_f32_16x16x32_bf16 v[104:107], v[48:51], v[196:199], 0
	v_mfma_f32_16x16x32_bf16 v[156:159], v[44:47], v[60:63], v[156:159]
	v_mfma_f32_16x16x32_bf16 v[152:155], v[52:55], v[60:63], v[152:155]
	v_mfma_f32_16x16x32_bf16 v[140:143], v[44:47], v[84:87], v[140:143]
	v_mfma_f32_16x16x32_bf16 v[136:139], v[52:55], v[84:87], v[136:139]
	v_mfma_f32_16x16x32_bf16 v[124:127], v[44:47], v[186:189], v[124:127]
	v_mfma_f32_16x16x32_bf16 v[120:123], v[52:55], v[186:189], v[120:123]
	v_mfma_f32_16x16x32_bf16 v[108:111], v[44:47], v[200:203], v[108:111]
	v_mfma_f32_16x16x32_bf16 v[104:107], v[52:55], v[200:203], v[104:107]
	s_setprio 0
	s_barrier
	s_add_i32 s60, 0, 0x14000
	v_add_u32_e32 v190, s60, v194
	s_add_i32 s24, s59, s36
	ds_read_b128 v[204:207], v190
	ds_read_b128 v[208:211], v190 offset:1024
	ds_read_b128 v[212:215], v190 offset:2048
	ds_read_b128 v[216:219], v190 offset:3072
	v_lshl_add_u64 v[190:191], s[8:9], 0, v[168:169]
	s_mov_b32 m0, s24
	v_lshl_add_u64 v[240:241], s[8:9], 0, v[164:165]
	global_load_lds_dwordx4 v[190:191], off
	s_add_i32 m0, s24, 0x2000
	s_nop 0
	global_load_lds_dwordx4 v[240:241], off
	s_barrier
	s_waitcnt lgkmcnt(0)
	s_setprio 1
	s_waitcnt lgkmcnt(0)
	v_mfma_f32_16x16x32_bf16 v[148:151], v[204:207], v[56:59], 0
	v_mfma_f32_16x16x32_bf16 v[56:59], v[212:215], v[56:59], 0
	v_mfma_f32_16x16x32_bf16 v[148:151], v[208:211], v[60:63], v[148:151]
	v_mfma_f32_16x16x32_bf16 v[56:59], v[216:219], v[60:63], v[56:59]
	v_mfma_f32_16x16x32_bf16 v[60:63], v[204:207], v[72:75], 0
	v_mfma_f32_16x16x32_bf16 v[72:75], v[212:215], v[72:75], 0
	v_mfma_f32_16x16x32_bf16 v[112:115], v[212:215], v[182:185], 0
	v_mfma_f32_16x16x32_bf16 v[100:103], v[204:207], v[196:199], 0
	v_mfma_f32_16x16x32_bf16 v[96:99], v[212:215], v[196:199], 0
	v_mfma_f32_16x16x32_bf16 v[60:63], v[208:211], v[84:87], v[60:63]
	v_mfma_f32_16x16x32_bf16 v[72:75], v[216:219], v[84:87], v[72:75]
	v_mfma_f32_16x16x32_bf16 v[84:87], v[204:207], v[182:185], 0
	v_mfma_f32_16x16x32_bf16 v[112:115], v[216:219], v[186:189], v[112:115]
	v_mfma_f32_16x16x32_bf16 v[100:103], v[208:211], v[200:203], v[100:103]
	v_mfma_f32_16x16x32_bf16 v[96:99], v[216:219], v[200:203], v[96:99]
	v_mfma_f32_16x16x32_bf16 v[84:87], v[208:211], v[186:189], v[84:87]
	s_setprio 0
	s_mov_b32 m0, s37
	v_lshl_add_u64 v[242:243], s[26:27], 0, v[160:161]
	s_barrier
	ds_read_b128 v[116:119], v195 offset:16384
	ds_read_b128 v[128:131], v195 offset:17408
	ds_read_b128 v[132:135], v195 offset:18432
	ds_read_b128 v[144:147], v195 offset:19456
	ds_read_b128 v[182:185], v195 offset:20480
	ds_read_b128 v[186:189], v195 offset:21504
	ds_read_b128 v[196:199], v195 offset:22528
	ds_read_b128 v[200:203], v195 offset:23552
	global_load_lds_dwordx4 v[242:243], off
	v_lshl_add_u64 v[244:245], s[26:27], 0, v[162:163]
	s_mov_b32 m0, s38
	s_nop 0
	global_load_lds_dwordx4 v[244:245], off
	s_barrier
	s_waitcnt lgkmcnt(0)
	s_setprio 1
	s_waitcnt lgkmcnt(0)
	v_mfma_f32_16x16x32_bf16 v[92:95], v[40:43], v[116:119], 0
	v_mfma_f32_16x16x32_bf16 v[88:91], v[48:51], v[116:119], 0
	v_mfma_f32_16x16x32_bf16 v[68:71], v[40:43], v[132:135], 0
	v_mfma_f32_16x16x32_bf16 v[64:67], v[48:51], v[132:135], 0
	v_mfma_f32_16x16x32_bf16 v[28:31], v[40:43], v[182:185], 0
	v_mfma_f32_16x16x32_bf16 v[24:27], v[48:51], v[182:185], 0
	v_mfma_f32_16x16x32_bf16 v[12:15], v[40:43], v[196:199], 0
	v_mfma_f32_16x16x32_bf16 v[8:11], v[48:51], v[196:199], 0
	v_mfma_f32_16x16x32_bf16 v[92:95], v[44:47], v[128:131], v[92:95]
	v_mfma_f32_16x16x32_bf16 v[88:91], v[52:55], v[128:131], v[88:91]
	v_mfma_f32_16x16x32_bf16 v[68:71], v[44:47], v[144:147], v[68:71]
	v_mfma_f32_16x16x32_bf16 v[64:67], v[52:55], v[144:147], v[64:67]
	v_mfma_f32_16x16x32_bf16 v[28:31], v[44:47], v[186:189], v[28:31]
	v_mfma_f32_16x16x32_bf16 v[24:27], v[52:55], v[186:189], v[24:27]
	v_mfma_f32_16x16x32_bf16 v[12:15], v[44:47], v[200:203], v[12:15]
	v_mfma_f32_16x16x32_bf16 v[8:11], v[52:55], v[200:203], v[8:11]
	s_setprio 0
	s_barrier
	s_add_u32 s24, s8, 0xb0000
	s_addc_u32 s25, s9, 0
	s_add_i32 s59, s60, s36
	v_lshl_add_u64 v[40:41], s[24:25], 0, v[168:169]
	s_mov_b32 m0, s59
	s_nop 0
	global_load_lds_dwordx4 v[40:41], off
	v_lshl_add_u64 v[40:41], s[24:25], 0, v[164:165]
	s_add_i32 m0, s59, 0x2000
	s_nop 0
	global_load_lds_dwordx4 v[40:41], off
	s_waitcnt vmcnt(6)
	s_barrier
	s_setprio 1
	v_mfma_f32_16x16x32_bf16 v[36:39], v[204:207], v[132:135], 0
	v_mfma_f32_16x16x32_bf16 v[32:35], v[212:215], v[132:135], 0
	v_mfma_f32_16x16x32_bf16 v[20:23], v[204:207], v[182:185], 0
	v_mfma_f32_16x16x32_bf16 v[16:19], v[212:215], v[182:185], 0
	v_mfma_f32_16x16x32_bf16 v[4:7], v[204:207], v[196:199], 0
	v_mfma_f32_16x16x32_bf16 v[0:3], v[212:215], v[196:199], 0
	v_mfma_f32_16x16x32_bf16 v[40:43], v[204:207], v[116:119], 0
	v_mfma_f32_16x16x32_bf16 v[44:47], v[212:215], v[116:119], 0
	v_mfma_f32_16x16x32_bf16 v[36:39], v[208:211], v[144:147], v[36:39]
	v_mfma_f32_16x16x32_bf16 v[32:35], v[216:219], v[144:147], v[32:35]
	v_mfma_f32_16x16x32_bf16 v[20:23], v[208:211], v[186:189], v[20:23]
	v_mfma_f32_16x16x32_bf16 v[16:19], v[216:219], v[186:189], v[16:19]
	v_mfma_f32_16x16x32_bf16 v[4:7], v[208:211], v[200:203], v[4:7]
	v_mfma_f32_16x16x32_bf16 v[0:3], v[216:219], v[200:203], v[0:3]
	v_mfma_f32_16x16x32_bf16 v[40:43], v[208:211], v[128:131], v[40:43]
	v_mfma_f32_16x16x32_bf16 v[44:47], v[216:219], v[128:131], v[44:47]
	s_setprio 0
	s_add_i32 s59, 0, 0x18000
	v_add_u32_e32 v80, s59, v194
	s_barrier
	ds_read_b128 v[48:51], v80
	ds_read_b128 v[52:55], v80 offset:1024
	ds_read_b128 v[76:79], v80 offset:2048
	ds_read_b128 v[80:83], v80 offset:3072
	s_add_u32 s24, s26, 0xb0000
	s_addc_u32 s25, s27, 0
	s_mov_b32 m0, s39
	v_lshl_add_u64 v[132:133], s[24:25], 0, v[160:161]
	ds_read_b128 v[116:119], v195 offset:32768
	ds_read_b128 v[128:131], v195 offset:33792
	ds_read_b128 v[182:185], v195 offset:34816
	ds_read_b128 v[186:189], v195 offset:35840
	ds_read_b128 v[196:199], v195 offset:36864
	ds_read_b128 v[200:203], v195 offset:37888
	ds_read_b128 v[204:207], v195 offset:38912
	ds_read_b128 v[208:211], v195 offset:39936
	global_load_lds_dwordx4 v[132:133], off
	v_lshl_add_u64 v[132:133], s[24:25], 0, v[162:163]
	s_mov_b32 m0, s40
	s_nop 0
	global_load_lds_dwordx4 v[132:133], off
	s_waitcnt lgkmcnt(8)
	s_barrier
	s_waitcnt lgkmcnt(0)
	s_setprio 1
	s_waitcnt lgkmcnt(0)
	v_mfma_f32_16x16x32_bf16 v[132:135], v[48:51], v[116:119], v[156:159]
	v_mfma_f32_16x16x32_bf16 v[156:159], v[52:55], v[128:131], v[132:135]
	v_mfma_f32_16x16x32_bf16 v[132:135], v[76:79], v[116:119], v[152:155]
	v_mfma_f32_16x16x32_bf16 v[152:155], v[80:83], v[128:131], v[132:135]
	v_mfma_f32_16x16x32_bf16 v[132:135], v[48:51], v[182:185], v[140:143]
	v_mfma_f32_16x16x32_bf16 v[140:143], v[52:55], v[186:189], v[132:135]
	v_mfma_f32_16x16x32_bf16 v[132:135], v[76:79], v[182:185], v[136:139]
	v_mfma_f32_16x16x32_bf16 v[124:127], v[48:51], v[196:199], v[124:127]
	v_mfma_f32_16x16x32_bf16 v[120:123], v[76:79], v[196:199], v[120:123]
	v_mfma_f32_16x16x32_bf16 v[108:111], v[48:51], v[204:207], v[108:111]
	v_mfma_f32_16x16x32_bf16 v[104:107], v[76:79], v[204:207], v[104:107]
	v_mfma_f32_16x16x32_bf16 v[136:139], v[80:83], v[186:189], v[132:135]
	v_mfma_f32_16x16x32_bf16 v[124:127], v[52:55], v[200:203], v[124:127]
	v_mfma_f32_16x16x32_bf16 v[120:123], v[80:83], v[200:203], v[120:123]
	v_mfma_f32_16x16x32_bf16 v[108:111], v[52:55], v[208:211], v[108:111]
	v_mfma_f32_16x16x32_bf16 v[104:107], v[80:83], v[208:211], v[104:107]
	s_setprio 0
	s_barrier
	s_add_i32 s24, 0, 0x1c000
	v_add_u32_e32 v132, s24, v194
	s_add_i32 s25, s59, s36
	ds_read_b128 v[212:215], v132
	ds_read_b128 v[216:219], v132 offset:1024
	ds_read_b128 v[220:223], v132 offset:2048
	ds_read_b128 v[236:239], v132 offset:3072
	v_lshl_add_u64 v[132:133], v[190:191], 0, s[78:79]
	s_mov_b32 m0, s25
	s_nop 0
	global_load_lds_dwordx4 v[132:133], off
	v_lshl_add_u64 v[132:133], v[240:241], 0, s[78:79]
	s_add_i32 m0, s25, 0x2000
	s_nop 0
	global_load_lds_dwordx4 v[132:133], off
	s_barrier
	s_waitcnt lgkmcnt(0)
	s_setprio 1
	s_waitcnt lgkmcnt(0)
	v_mfma_f32_16x16x32_bf16 v[56:59], v[220:223], v[116:119], v[56:59]
	v_mfma_f32_16x16x32_bf16 v[132:135], v[212:215], v[116:119], v[148:151]
	v_mfma_f32_16x16x32_bf16 v[144:147], v[236:239], v[128:131], v[56:59]
	v_mfma_f32_16x16x32_bf16 v[56:59], v[212:215], v[182:185], v[60:63]
	v_mfma_f32_16x16x32_bf16 v[148:151], v[216:219], v[128:131], v[132:135]
	v_mfma_f32_16x16x32_bf16 v[132:135], v[216:219], v[186:189], v[56:59]
	v_mfma_f32_16x16x32_bf16 v[56:59], v[220:223], v[182:185], v[72:75]
	v_mfma_f32_16x16x32_bf16 v[128:131], v[236:239], v[186:189], v[56:59]
	v_mfma_f32_16x16x32_bf16 v[56:59], v[212:215], v[196:199], v[84:87]
	v_mfma_f32_16x16x32_bf16 v[116:119], v[216:219], v[200:203], v[56:59]
	v_mfma_f32_16x16x32_bf16 v[56:59], v[220:223], v[196:199], v[112:115]
	v_mfma_f32_16x16x32_bf16 v[112:115], v[236:239], v[200:203], v[56:59]
	v_mfma_f32_16x16x32_bf16 v[56:59], v[212:215], v[204:207], v[100:103]
	v_mfma_f32_16x16x32_bf16 v[100:103], v[216:219], v[208:211], v[56:59]
	v_mfma_f32_16x16x32_bf16 v[56:59], v[220:223], v[204:207], v[96:99]
	v_mfma_f32_16x16x32_bf16 v[96:99], v[236:239], v[208:211], v[56:59]
	s_setprio 0
	s_mov_b32 m0, s47
	v_lshl_add_u64 v[190:191], v[242:243], 0, s[78:79]
	s_barrier
	s_nop 2
	ds_read_b128 v[56:59], v195 offset:49152
	ds_read_b128 v[60:63], v195 offset:50176
	ds_read_b128 v[72:75], v195 offset:51200
	ds_read_b128 v[84:87], v195 offset:52224
	ds_read_b128 v[182:185], v195 offset:53248
	ds_read_b128 v[186:189], v195 offset:54272
	ds_read_b128 v[196:199], v195 offset:55296
	ds_read_b128 v[200:203], v195 offset:56320
	global_load_lds_dwordx4 v[190:191], off
	v_lshl_add_u64 v[190:191], v[244:245], 0, s[78:79]
	s_mov_b32 m0, s49
	s_nop 0
	global_load_lds_dwordx4 v[190:191], off
	s_barrier
	s_waitcnt lgkmcnt(0)
	s_setprio 1
	s_waitcnt lgkmcnt(0)
	v_mfma_f32_16x16x32_bf16 v[92:95], v[48:51], v[56:59], v[92:95]
	v_mfma_f32_16x16x32_bf16 v[88:91], v[76:79], v[56:59], v[88:91]
	v_mfma_f32_16x16x32_bf16 v[68:71], v[48:51], v[72:75], v[68:71]
	v_mfma_f32_16x16x32_bf16 v[64:67], v[76:79], v[72:75], v[64:67]
	v_mfma_f32_16x16x32_bf16 v[28:31], v[48:51], v[182:185], v[28:31]
	v_mfma_f32_16x16x32_bf16 v[24:27], v[76:79], v[182:185], v[24:27]
	v_mfma_f32_16x16x32_bf16 v[12:15], v[48:51], v[196:199], v[12:15]
	v_mfma_f32_16x16x32_bf16 v[8:11], v[76:79], v[196:199], v[8:11]
	v_mfma_f32_16x16x32_bf16 v[92:95], v[52:55], v[60:63], v[92:95]
	v_mfma_f32_16x16x32_bf16 v[88:91], v[80:83], v[60:63], v[88:91]
	v_mfma_f32_16x16x32_bf16 v[68:71], v[52:55], v[84:87], v[68:71]
	v_mfma_f32_16x16x32_bf16 v[64:67], v[80:83], v[84:87], v[64:67]
	v_mfma_f32_16x16x32_bf16 v[28:31], v[52:55], v[186:189], v[28:31]
	v_mfma_f32_16x16x32_bf16 v[24:27], v[80:83], v[186:189], v[24:27]
	v_mfma_f32_16x16x32_bf16 v[12:15], v[52:55], v[200:203], v[12:15]
	v_mfma_f32_16x16x32_bf16 v[8:11], v[80:83], v[200:203], v[8:11]
	s_setprio 0
	s_barrier
	s_add_u32 s8, s8, 0xb0080
	s_addc_u32 s9, s9, 0
	s_add_i32 s24, s24, s36
	v_lshl_add_u64 v[48:49], s[8:9], 0, v[168:169]
	s_mov_b32 m0, s24
	s_nop 0
	global_load_lds_dwordx4 v[48:49], off
	v_lshl_add_u64 v[48:49], s[8:9], 0, v[164:165]
	s_add_i32 m0, s24, 0x2000
	s_nop 0
	global_load_lds_dwordx4 v[48:49], off
	s_waitcnt vmcnt(6)
	s_barrier
	s_setprio 1
	v_mfma_f32_16x16x32_bf16 v[40:43], v[212:215], v[56:59], v[40:43]
	v_mfma_f32_16x16x32_bf16 v[80:83], v[216:219], v[60:63], v[40:43]
	v_mfma_f32_16x16x32_bf16 v[40:43], v[220:223], v[56:59], v[44:47]
	v_mfma_f32_16x16x32_bf16 v[36:39], v[212:215], v[72:75], v[36:39]
	v_mfma_f32_16x16x32_bf16 v[32:35], v[220:223], v[72:75], v[32:35]
	v_mfma_f32_16x16x32_bf16 v[20:23], v[212:215], v[182:185], v[20:23]
	v_mfma_f32_16x16x32_bf16 v[16:19], v[220:223], v[182:185], v[16:19]
	v_mfma_f32_16x16x32_bf16 v[4:7], v[212:215], v[196:199], v[4:7]
	v_mfma_f32_16x16x32_bf16 v[0:3], v[220:223], v[196:199], v[0:3]
	v_mfma_f32_16x16x32_bf16 v[76:79], v[236:239], v[60:63], v[40:43]
	v_mfma_f32_16x16x32_bf16 v[36:39], v[216:219], v[84:87], v[36:39]
	v_mfma_f32_16x16x32_bf16 v[32:35], v[236:239], v[84:87], v[32:35]
	v_mfma_f32_16x16x32_bf16 v[20:23], v[216:219], v[186:189], v[20:23]
	v_mfma_f32_16x16x32_bf16 v[16:19], v[236:239], v[186:189], v[16:19]
	v_mfma_f32_16x16x32_bf16 v[4:7], v[216:219], v[200:203], v[4:7]
	v_mfma_f32_16x16x32_bf16 v[0:3], v[236:239], v[200:203], v[0:3]
	s_setprio 0
	s_add_i32 s58, s58, 2
	s_add_u32 s56, s56, 0x100
	s_addc_u32 s57, s57, 0
	s_cmp_gt_u32 s58, 41
	s_mov_b64 s[24:25], s[2:3]
	s_barrier
